# K-loop first iteration after an epilogue skips phase-1/2 vmcnt waits (MLP1, gemm_in) so the store drain overlaps two MMA blocks
# speedup vs baseline: 1.0043x; 1.0043x over previous
;     ...
;   const int tid = opaque_tid(), wid = __builtin_amdgcn_readfirstlane(tid >> 6), lane = tid & 63, wr = wid >> 2, wc = wid & 3;
;   constexpr int nt = K / BK;
;   unsigned voff[2], voffB[2];
; #pragma unroll
;   for (int i = 0; i < 2; ++i) {
;     int r_, c_;
;     stage_rc(tid * 16 + i * 8192, r_, c_);
;     voff[i] = (unsigned)(r_ * K + c_) * 2u;
;     const int rho = r_ & 31, nn = rho >> 4, ii = rho & 15;
;     const int rb = (r_ & ~31) + 8 * (ii >> 2) + 4 * nn + (ii & 3);
;     voffB[i] = (unsigned)(rb * K + c_) * 2u;
;   }
;   const size_t kstep = (size_t)(BK * 2);
;   const size_t hstep = (size_t)HALF * K * 2;
;   const size_t tstep = 2 * hstep;
;   const unsigned ldsw = (unsigned)wid * 1024u;
;   const int aoff = lds_byte(wr * 64 + (lane & 15), (lane >> 4) * 8), boff = lds_byte(wc * 32 + (lane & 15), (lane >> 4) * 8);
;   auto unit = [&](int i, int& pm, int& pn, int& kq) -> bool {
;     const long L = (long)i * gridDim.x + blockIdx.x;
;     kq = -1;
;     if (SPLIT && L >= nwg) {
;       const int u = (int)(L - nwg);
;       if (u >= 16 * nMsplit) return false;
;       pm = nM + (u >> 4); pn = (u >> 2) & 3; kq = u & 3;
;       return true;
;     }
;     if (L >= nwg) return false;
;     int wgid = (int)L;
;     {
;       const int q = nwg / NXCD, r = nwg % NXCD, xcd = wgid % NXCD, off = wgid / NXCD;
;       wgid = (xcd < r ? xcd * (q + 1) : r * (q + 1) + (xcd - r) * q) + off;
;     }
;     const int nig = WGM * nN, gid = wgid / nig, fm = gid * WGM, gsz = min(nM - fm, WGM);
;     pm = fm + ((wgid % nig) % gsz);
;     pn = (wgid % nig) / gsz;
;     return true;
;   };
;   int pm, pn, kq, npm = 0, npn = 0, nkq = -1, ui = 0;
;   if (!unit(0, pm, pn, kq)) return;
;   const char* cA = (const char*)A + (size_t)pm * tstep + (kq > 0 ? (size_t)kq * (K / 4) * 2 : 0);
;   const char* cB = (const char*)Bt + (size_t)pn * tstep + (kq > 0 ? (size_t)kq * (K / 4) * 2 : 0);
;   f32x4 acc[2][2][4][2];
; #pragma unroll
;   for (int a = 0; a < 2; ++a)
; #pragma unroll
;     for (int b = 0; b < 2; ++b)
; #pragma unroll
;       for (int m = 0; m < 4; ++m)
; #pragma unroll
;         for (int n = 0; n < 2; ++n) acc[a][b][m][n] = (f32x4){0.f, 0.f, 0.f, 0.f};
;   bf16x8 At[4][2], B0[2][2], B1[2][2];
;   STAGE(SBo(0, 0), cB, voffB); STAGE(SBo(0, 1), cB + hstep, voffB); STAGE(SAo(0, 0), cA, voff); STAGE(SAo(0, 1), cA + hstep, voff);
;   if (wr == 1) BAR;
;   WAIT_V(2); BAR;
.LBB0_143:
	s_or_b64 exec, exec, s[0:1]
	v_readlane_b32 s0, v254, 34
	v_readlane_b32 s1, v254, 35
	s_lshl_b32 s2, s96, 6
	s_mov_b32 s3, s1
	v_readlane_b32 s0, v253, 35
	v_writelane_b32 v255, s2, 1
	v_mov_b32_e32 v0, v234
	v_readlane_b32 s1, v253, 36
	s_waitcnt lgkmcnt(0)
	s_barrier
	v_writelane_b32 v255, s3, 2
	s_mov_b32 s100, 0
	s_andn2_b64 vcc, exec, s[0:1]
	v_readfirstlane_b32 s0, v0
	s_cbranch_vccnz .LBB0_377
	v_lshlrev_b32_e32 v2, 4, v0
	v_add_u32_e32 v3, 0x2000, v2
	v_ashrrev_i32_e32 v4, 31, v3
	v_lshrrev_b32_e32 v4, 22, v4
	v_add_u32_e32 v4, v3, v4
	s_waitcnt vmcnt(10)
	v_ashrrev_i32_e32 v6, 10, v4
	v_mul_i32_i24_e32 v4, 0x400, v6
	v_sub_u32_e32 v3, v3, v4
	v_lshrrev_b32_e32 v4, 4, v3
	v_bitop3_b32 v3, v4, v3, 32 bitop3:0x6c
	v_ashrrev_i32_e32 v4, 31, v3
	v_readlane_b32 s4, v252, 0
	v_lshrrev_b32_e32 v4, 26, v4
	v_readlane_b32 s2, v254, 34
	v_readlane_b32 s8, v252, 4
	v_readlane_b32 s9, v252, 5
	v_readlane_b32 s10, v252, 6
	v_readlane_b32 s11, v252, 7
	v_readlane_b32 s12, v252, 8
	v_readlane_b32 s13, v252, 9
	v_readlane_b32 s14, v252, 10
	v_readlane_b32 s15, v252, 11
	v_add_u32_e32 v4, v3, v4
	v_lshlrev_b32_e32 v5, 3, v6
	v_readlane_b32 s3, v254, 35
	s_mul_i32 s2, s96, 0x380000
	v_readlane_b32 s16, v252, 12
	v_readlane_b32 s17, v252, 13
	v_readlane_b32 s18, v252, 14
	v_readlane_b32 s19, v252, 15
	s_mov_b64 s[8:9], s[12:13]
	v_ashrrev_i32_e32 v7, 6, v4
	v_and_b32_e32 v5, -16, v5
	s_mov_b32 s21, s3
	s_lshl_b64 s[2:3], s[2:3], 1
	v_readlane_b32 s6, v252, 2
	s_mov_b64 s[10:11], s[14:15]
	v_add_u32_e32 v5, v7, v5
	s_add_u32 s6, s10, s2
	v_and_b32_e32 v8, 3, v7
	s_mov_b32 s2, 0x1fffe0
	v_lshlrev_b32_e32 v9, 1, v5
	v_lshrrev_b32_e32 v10, 2, v5
	v_and_b32_e32 v4, 0xc0, v4
	v_and_or_b32 v8, v5, s2, v8
	v_and_b32_e32 v9, 24, v9
	v_and_b32_e32 v10, 4, v10
	v_sub_u32_e32 v3, v3, v4
	v_or3_b32 v9, v8, v9, v10
	v_lshlrev_b32_e32 v8, 5, v6
	v_ashrrev_i16_sdwa v3, v237, sext(v3) dst_sel:DWORD dst_unused:UNUSED_PAD src0_sel:DWORD src1_sel:BYTE_0
	v_and_b32_e32 v10, 32, v8
	v_bfe_i32 v8, v3, 0, 16
	v_add_lshl_u32 v3, v10, v8, 1
	s_waitcnt vmcnt(4)
	v_lshl_add_u32 v142, v9, 11, v3
	v_lshl_add_u32 v144, v5, 11, v3
	v_bfe_i32 v3, v0, 27, 1
	v_lshrrev_b32_e32 v3, 22, v3
	v_add_u32_e32 v3, v2, v3
	v_and_b32_e32 v3, 0xfffffc00, v3
	v_sub_u32_e32 v2, v2, v3
	v_lshrrev_b32_e32 v3, 4, v2
	v_bitop3_b32 v3, v3, v2, 32 bitop3:0x6c
	v_ashrrev_i32_e32 v2, 31, v2
	v_lshrrev_b32_e32 v2, 26, v2
	v_add_u32_e32 v2, v3, v2
	v_ashrrev_i32_e32 v9, 6, v2
	v_ashrrev_i32_e32 v2, 31, v0
	v_lshrrev_b32_e32 v2, 26, v2
	v_add_u32_e32 v2, v0, v2
	v_ashrrev_i32_e32 v10, 6, v2
	v_lshlrev_b32_e32 v2, 3, v10
	v_and_b32_e32 v2, -16, v2
	v_add_u32_e32 v2, v9, v2
	v_and_b32_e32 v4, 3, v9
	v_lshlrev_b32_e32 v5, 1, v2
	v_lshrrev_b32_e32 v11, 2, v2
	v_and_or_b32 v4, v2, s2, v4
	v_and_b32_e32 v5, 24, v5
	v_and_b32_e32 v11, 4, v11
	v_readlane_b32 s7, v252, 3
	v_or3_b32 v4, v4, v5, v11
	v_mul_i32_i24_e32 v11, 64, v9
	s_addc_u32 s7, s11, s3
	s_ashr_i32 s4, s0, 6
	v_sub_u32_e32 v3, v3, v11
	s_ashr_i32 s1, s0, 8
	s_lshl_b32 s8, s4, 10
	v_lshlrev_b32_e32 v5, 5, v10
	v_ashrrev_i16_sdwa v3, v237, sext(v3) dst_sel:DWORD dst_unused:UNUSED_PAD src0_sel:DWORD src1_sel:BYTE_0
	v_readlane_b32 s2, v253, 46
	v_and_b32_e32 v5, 32, v5
	v_bfe_i32 v11, v3, 0, 16
	s_add_u32 s2, s6, s2
	v_add_lshl_u32 v3, v5, v11, 1
	s_addc_u32 s3, s7, 0
	s_add_i32 s9, s8, 0
	v_lshl_add_u32 v146, v4, 11, v3
	s_add_i32 m0, s9, 0x10000
	s_mov_b64 s[12:13], s[16:17]
	global_load_lds_dwordx4 v146, s[2:3]
	s_add_i32 m0, s9, 0x12000
	s_add_u32 s10, s2, 0x40000
	global_load_lds_dwordx4 v142, s[2:3]
	s_addc_u32 s11, s3, 0
	s_add_i32 m0, s9, 0x14000
	s_mov_b64 s[14:15], s[18:19]
	global_load_lds_dwordx4 v146, s[10:11]
	s_add_i32 m0, s9, 0x16000
	v_readlane_b32 s12, v253, 47
	v_lshl_add_u32 v148, v2, 11, v3
	global_load_lds_dwordx4 v142, s[10:11]
	s_mov_b32 m0, s9
	v_readlane_b32 s13, v253, 48
	s_add_i32 s10, s9, 0x2000
	s_add_i32 s11, s9, 0x4000
	v_readlane_b32 s14, v253, 49
	v_readlane_b32 s15, v253, 50
	v_mov_b32_e32 v147, v1
	global_load_lds_dwordx4 v148, s[12:13]
	s_mov_b32 m0, s10
	v_mov_b32_e32 v143, v1
	global_load_lds_dwordx4 v144, s[12:13]
	s_mov_b32 m0, s11
	s_add_i32 s12, s9, 0x6000
	global_load_lds_dwordx4 v148, s[14:15]
	s_mov_b32 m0, s12
	s_cmp_eq_u32 s1, 1
	global_load_lds_dwordx4 v144, s[14:15]
	v_lshl_add_u64 v[2:3], s[2:3], 0, v[146:147]
	s_cselect_b64 s[44:45], -1, 0
	s_cmp_lg_u32 s1, 1
	v_lshl_add_u64 v[4:5], s[2:3], 0, v[142:143]
	v_readlane_b32 s5, v252, 1
	s_cbranch_scc1 .LBB0_146
	s_barrier

; #define WAIT_V(n) asm volatile("s_waitcnt vmcnt(" #n ")" ::: "memory")
; #define WAIT_L(n) asm volatile("s_waitcnt lgkmcnt(" #n ")" ::: "memory")
; #define BAR __builtin_amdgcn_s_barrier()
; #define SCHED __builtin_amdgcn_sched_barrier(0)
;     ...
;       LDB(B0, 0, 0); LDB(B1, 0, 1); SCHED; LDA(At, 0, 0); STAGE(SAo(1, 1), a1 + hstep, voff);
;       WAIT_V(8); WAIT_L(0); BAR; MMA(0, 0, At, B0); MMA(0, 1, At, B1); BAR; SCHED;
;       LDA(At, 0, 1); STAGE(SBo(0, 0), b2, voffB); STAGE(SBo(0, 1), b2 + hstep, voffB); STAGE(SAo(0, 0), a2, voff);
;       WAIT_V(8); WAIT_L(0); BAR; MMA(1, 0, At, B0); MMA(1, 1, At, B1); BAR; SCHED;
.LBB0_152:
	s_add_u32 s2, s0, 0xfffc0080
	s_addc_u32 s3, s1, -1
	s_add_i32 s31, 0, 0x10000
	s_cmp_eq_u32 s30, 12
	s_cselect_b32 s5, s22, s3
	s_cselect_b32 s4, s25, s2
	v_add_u32_e32 v0, s31, v158
	s_cselect_b32 s3, s26, s29
	s_cselect_b32 s2, s27, s28
	s_add_i32 s33, 0, 0x14000
	ds_read_b128 v[130:133], v0
	ds_read_b128 v[134:137], v0 offset:1024
	ds_read_b128 v[138:141], v0 offset:2048
	ds_read_b128 v[154:157], v0 offset:3072
	v_add_u32_e32 v0, s33, v158
	ds_read_b128 v[160:163], v0
	ds_read_b128 v[164:167], v0 offset:1024
	ds_read_b128 v[168:171], v0 offset:2048
	ds_read_b128 v[178:181], v0 offset:3072
	v_lshl_add_u64 v[214:215], s[0:1], 0, v[150:151]
	s_add_i32 m0, s9, 0xc000
	ds_read_b128 v[182:185], v159
	ds_read_b128 v[186:189], v159 offset:1024
	ds_read_b128 v[190:193], v159 offset:2048
	ds_read_b128 v[194:197], v159 offset:3072
	ds_read_b128 v[198:201], v159 offset:4096
	ds_read_b128 v[202:205], v159 offset:5120
	ds_read_b128 v[206:209], v159 offset:6144
	ds_read_b128 v[210:213], v159 offset:7168
	global_load_lds_dwordx4 v[214:215], off
	v_lshl_add_u64 v[214:215], s[0:1], 0, v[152:153]
	s_add_i32 m0, s9, 0xe000
	s_nop 0
	global_load_lds_dwordx4 v[214:215], off
	s_cmp_lg_u32 s100, 0
	s_cbranch_scc1 .Lkp_gi_0
	s_waitcnt vmcnt(8)
.Lkp_gi_0:
	s_waitcnt lgkmcnt(0)
	s_barrier
	s_setprio 1
	s_waitcnt lgkmcnt(0)
	v_mfma_f32_16x16x32_bf16 v[126:129], v[130:133], v[182:185], v[126:129]
	v_mfma_f32_16x16x32_bf16 v[122:125], v[138:141], v[182:185], v[122:125]
	v_mfma_f32_16x16x32_bf16 v[110:113], v[130:133], v[190:193], v[110:113]
	v_mfma_f32_16x16x32_bf16 v[106:109], v[138:141], v[190:193], v[106:109]
	v_mfma_f32_16x16x32_bf16 v[94:97], v[130:133], v[198:201], v[94:97]
	v_mfma_f32_16x16x32_bf16 v[90:93], v[138:141], v[198:201], v[90:93]
	v_mfma_f32_16x16x32_bf16 v[78:81], v[130:133], v[206:209], v[78:81]
	v_mfma_f32_16x16x32_bf16 v[74:77], v[138:141], v[206:209], v[74:77]
	v_mfma_f32_16x16x32_bf16 v[126:129], v[134:137], v[186:189], v[126:129]
	v_mfma_f32_16x16x32_bf16 v[122:125], v[154:157], v[186:189], v[122:125]
	v_mfma_f32_16x16x32_bf16 v[110:113], v[134:137], v[194:197], v[110:113]
	v_mfma_f32_16x16x32_bf16 v[106:109], v[154:157], v[194:197], v[106:109]
	v_mfma_f32_16x16x32_bf16 v[94:97], v[134:137], v[202:205], v[94:97]
	v_mfma_f32_16x16x32_bf16 v[90:93], v[154:157], v[202:205], v[90:93]
	v_mfma_f32_16x16x32_bf16 v[78:81], v[134:137], v[210:213], v[78:81]
	v_mfma_f32_16x16x32_bf16 v[74:77], v[154:157], v[210:213], v[74:77]
	s_setprio 0
	s_setprio 1
	v_mfma_f32_16x16x32_bf16 v[118:121], v[160:163], v[182:185], v[118:121]
	v_mfma_f32_16x16x32_bf16 v[114:117], v[168:171], v[182:185], v[114:117]
	v_mfma_f32_16x16x32_bf16 v[102:105], v[160:163], v[190:193], v[102:105]
	v_mfma_f32_16x16x32_bf16 v[98:101], v[168:171], v[190:193], v[98:101]
	v_mfma_f32_16x16x32_bf16 v[86:89], v[160:163], v[198:201], v[86:89]
	v_mfma_f32_16x16x32_bf16 v[82:85], v[168:171], v[198:201], v[82:85]
	v_mfma_f32_16x16x32_bf16 v[70:73], v[160:163], v[206:209], v[70:73]
	v_mfma_f32_16x16x32_bf16 v[66:69], v[168:171], v[206:209], v[66:69]
	v_mfma_f32_16x16x32_bf16 v[118:121], v[164:167], v[186:189], v[118:121]
	v_mfma_f32_16x16x32_bf16 v[114:117], v[178:181], v[186:189], v[114:117]
	v_mfma_f32_16x16x32_bf16 v[102:105], v[164:167], v[194:197], v[102:105]
	v_mfma_f32_16x16x32_bf16 v[98:101], v[178:181], v[194:197], v[98:101]
	v_mfma_f32_16x16x32_bf16 v[86:89], v[164:167], v[202:205], v[86:89]
	v_mfma_f32_16x16x32_bf16 v[82:85], v[178:181], v[202:205], v[82:85]
	v_mfma_f32_16x16x32_bf16 v[70:73], v[164:167], v[210:213], v[70:73]
	v_mfma_f32_16x16x32_bf16 v[66:69], v[178:181], v[210:213], v[66:69]
	s_setprio 0
	s_barrier
	s_add_i32 s31, s31, s8
	v_lshl_add_u64 v[214:215], s[2:3], 0, v[146:147]
	s_mov_b32 m0, s31
	ds_read_b128 v[182:185], v159 offset:16384
	ds_read_b128 v[186:189], v159 offset:17408
	ds_read_b128 v[190:193], v159 offset:18432
	ds_read_b128 v[194:197], v159 offset:19456
	ds_read_b128 v[198:201], v159 offset:20480
	ds_read_b128 v[202:205], v159 offset:21504
	ds_read_b128 v[206:209], v159 offset:22528
	ds_read_b128 v[210:213], v159 offset:23552
	global_load_lds_dwordx4 v[214:215], off
	s_add_i32 m0, s31, 0x2000
	s_add_u32 s40, s2, 0x40000
	v_lshl_add_u64 v[216:217], s[2:3], 0, v[142:143]
	s_addc_u32 s41, s3, 0
	s_add_i32 s31, s33, s8
	global_load_lds_dwordx4 v[216:217], off
	v_lshl_add_u64 v[218:219], s[40:41], 0, v[146:147]
	s_mov_b32 m0, s31
	v_lshl_add_u64 v[220:221], s[4:5], 0, v[144:145]
	global_load_lds_dwordx4 v[218:219], off
	v_lshl_add_u64 v[218:219], s[40:41], 0, v[142:143]
	s_add_i32 m0, s31, 0x2000
	s_nop 0
	global_load_lds_dwordx4 v[218:219], off
	v_lshl_add_u64 v[218:219], s[4:5], 0, v[148:149]
	s_mov_b32 m0, s9
	s_nop 0
	global_load_lds_dwordx4 v[218:219], off
	s_mov_b32 m0, s10
	s_nop 0
	global_load_lds_dwordx4 v[220:221], off
	s_cmp_lg_u32 s100, 0
	s_cbranch_scc1 .Lkp_gi_1
	s_waitcnt vmcnt(8)
; #define WAIT_V(n) asm volatile("s_waitcnt vmcnt(" #n ")" ::: "memory")
; #define WAIT_L(n) asm volatile("s_waitcnt lgkmcnt(" #n ")" ::: "memory")
; #define BAR __builtin_amdgcn_s_barrier()
; #define SCHED __builtin_amdgcn_sched_barrier(0)
;     ...
;       WAIT_V(8); WAIT_L(0); BAR; MMA(0, 0, At, B0); MMA(0, 1, At, B1); BAR; SCHED;
;       LDA(At, 0, 1); STAGE(SBo(0, 0), b2, voffB); STAGE(SBo(0, 1), b2 + hstep, voffB); STAGE(SAo(0, 0), a2, voff);
;       WAIT_V(8); WAIT_L(0); BAR; MMA(1, 0, At, B0); MMA(1, 1, At, B1); BAR; SCHED;
;       LDB(B0, 1, 0); LDB(B1, 1, 1); SCHED; LDA(At, 1, 0); STAGE(SAo(0, 1), a2 + hstep, voff);
;       WAIT_V(8); WAIT_L(0); BAR; MMA(0, 0, At, B0); MMA(0, 1, At, B1); BAR; SCHED;
.Lkp_gi_1:
	s_mov_b32 s100, 0
	s_waitcnt lgkmcnt(0)
	s_barrier
	s_setprio 1
	s_waitcnt lgkmcnt(0)
	v_mfma_f32_16x16x32_bf16 v[62:65], v[130:133], v[182:185], v[62:65]
	v_mfma_f32_16x16x32_bf16 v[58:61], v[138:141], v[182:185], v[58:61]
	v_mfma_f32_16x16x32_bf16 v[46:49], v[130:133], v[190:193], v[46:49]
	v_mfma_f32_16x16x32_bf16 v[42:45], v[138:141], v[190:193], v[42:45]
	v_mfma_f32_16x16x32_bf16 v[30:33], v[130:133], v[198:201], v[30:33]
	v_mfma_f32_16x16x32_bf16 v[26:29], v[138:141], v[198:201], v[26:29]
	v_mfma_f32_16x16x32_bf16 v[14:17], v[130:133], v[206:209], v[14:17]
	v_mfma_f32_16x16x32_bf16 v[10:13], v[138:141], v[206:209], v[10:13]
	v_mfma_f32_16x16x32_bf16 v[62:65], v[134:137], v[186:189], v[62:65]
	v_mfma_f32_16x16x32_bf16 v[58:61], v[154:157], v[186:189], v[58:61]
	v_mfma_f32_16x16x32_bf16 v[46:49], v[134:137], v[194:197], v[46:49]
	v_mfma_f32_16x16x32_bf16 v[42:45], v[154:157], v[194:197], v[42:45]
	v_mfma_f32_16x16x32_bf16 v[30:33], v[134:137], v[202:205], v[30:33]
	v_mfma_f32_16x16x32_bf16 v[26:29], v[154:157], v[202:205], v[26:29]
	v_mfma_f32_16x16x32_bf16 v[14:17], v[134:137], v[210:213], v[14:17]
	v_mfma_f32_16x16x32_bf16 v[10:13], v[154:157], v[210:213], v[10:13]
	s_setprio 0
	s_setprio 1
	v_mfma_f32_16x16x32_bf16 v[54:57], v[160:163], v[182:185], v[54:57]
	v_mfma_f32_16x16x32_bf16 v[50:53], v[168:171], v[182:185], v[50:53]
	v_mfma_f32_16x16x32_bf16 v[38:41], v[160:163], v[190:193], v[38:41]
	v_mfma_f32_16x16x32_bf16 v[34:37], v[168:171], v[190:193], v[34:37]
	v_mfma_f32_16x16x32_bf16 v[22:25], v[160:163], v[198:201], v[22:25]
	v_mfma_f32_16x16x32_bf16 v[18:21], v[168:171], v[198:201], v[18:21]
	v_mfma_f32_16x16x32_bf16 v[6:9], v[160:163], v[206:209], v[6:9]
	v_mfma_f32_16x16x32_bf16 v[2:5], v[168:171], v[206:209], v[2:5]
	v_mfma_f32_16x16x32_bf16 v[54:57], v[164:167], v[186:189], v[54:57]
	v_mfma_f32_16x16x32_bf16 v[50:53], v[178:181], v[186:189], v[50:53]
	v_mfma_f32_16x16x32_bf16 v[38:41], v[164:167], v[194:197], v[38:41]
	v_mfma_f32_16x16x32_bf16 v[34:37], v[178:181], v[194:197], v[34:37]
	v_mfma_f32_16x16x32_bf16 v[22:25], v[164:167], v[202:205], v[22:25]
	v_mfma_f32_16x16x32_bf16 v[18:21], v[178:181], v[202:205], v[18:21]
	v_mfma_f32_16x16x32_bf16 v[6:9], v[164:167], v[210:213], v[6:9]
	v_mfma_f32_16x16x32_bf16 v[2:5], v[178:181], v[210:213], v[2:5]
	s_setprio 0
	s_barrier
	s_add_i32 s31, 0, 0x18000
	v_add_u32_e32 v0, s31, v158
	s_add_i32 s33, 0, 0x1c000
	ds_read_b128 v[130:133], v0
	ds_read_b128 v[134:137], v0 offset:1024
	ds_read_b128 v[138:141], v0 offset:2048
	ds_read_b128 v[154:157], v0 offset:3072
	v_add_u32_e32 v0, s33, v158
	ds_read_b128 v[160:163], v0
	ds_read_b128 v[164:167], v0 offset:1024
	ds_read_b128 v[168:171], v0 offset:2048
	ds_read_b128 v[178:181], v0 offset:3072
	s_add_u32 s4, s4, 0x40000
	s_addc_u32 s5, s5, 0
	s_mov_b32 m0, s11
	v_lshl_add_u64 v[222:223], s[4:5], 0, v[148:149]
	ds_read_b128 v[182:185], v159 offset:32768
	ds_read_b128 v[186:189], v159 offset:33792
	ds_read_b128 v[190:193], v159 offset:34816
	ds_read_b128 v[194:197], v159 offset:35840
	ds_read_b128 v[198:201], v159 offset:36864
	ds_read_b128 v[202:205], v159 offset:37888
	ds_read_b128 v[206:209], v159 offset:38912
	ds_read_b128 v[210:213], v159 offset:39936
	global_load_lds_dwordx4 v[222:223], off
	v_lshl_add_u64 v[222:223], s[4:5], 0, v[144:145]
	s_mov_b32 m0, s12
	s_nop 0
	global_load_lds_dwordx4 v[222:223], off
	s_waitcnt vmcnt(8)
	s_waitcnt lgkmcnt(0)
	s_barrier
	s_setprio 1
	s_waitcnt lgkmcnt(0)
	v_mfma_f32_16x16x32_bf16 v[126:129], v[130:133], v[182:185], v[126:129]
	v_mfma_f32_16x16x32_bf16 v[122:125], v[138:141], v[182:185], v[122:125]
	v_mfma_f32_16x16x32_bf16 v[110:113], v[130:133], v[190:193], v[110:113]
	v_mfma_f32_16x16x32_bf16 v[106:109], v[138:141], v[190:193], v[106:109]
	v_mfma_f32_16x16x32_bf16 v[94:97], v[130:133], v[198:201], v[94:97]
	v_mfma_f32_16x16x32_bf16 v[90:93], v[138:141], v[198:201], v[90:93]
	v_mfma_f32_16x16x32_bf16 v[78:81], v[130:133], v[206:209], v[78:81]
	v_mfma_f32_16x16x32_bf16 v[74:77], v[138:141], v[206:209], v[74:77]
	v_mfma_f32_16x16x32_bf16 v[126:129], v[134:137], v[186:189], v[126:129]
	v_mfma_f32_16x16x32_bf16 v[122:125], v[154:157], v[186:189], v[122:125]
	v_mfma_f32_16x16x32_bf16 v[110:113], v[134:137], v[194:197], v[110:113]
	v_mfma_f32_16x16x32_bf16 v[106:109], v[154:157], v[194:197], v[106:109]
	v_mfma_f32_16x16x32_bf16 v[94:97], v[134:137], v[202:205], v[94:97]
	v_mfma_f32_16x16x32_bf16 v[90:93], v[154:157], v[202:205], v[90:93]
	v_mfma_f32_16x16x32_bf16 v[78:81], v[134:137], v[210:213], v[78:81]
	v_mfma_f32_16x16x32_bf16 v[74:77], v[154:157], v[210:213], v[74:77]
	s_setprio 0
	s_setprio 1
	v_mfma_f32_16x16x32_bf16 v[118:121], v[160:163], v[182:185], v[118:121]
	v_mfma_f32_16x16x32_bf16 v[114:117], v[168:171], v[182:185], v[114:117]
	v_mfma_f32_16x16x32_bf16 v[102:105], v[160:163], v[190:193], v[102:105]
	v_mfma_f32_16x16x32_bf16 v[98:101], v[168:171], v[190:193], v[98:101]
	v_mfma_f32_16x16x32_bf16 v[86:89], v[160:163], v[198:201], v[86:89]
	v_mfma_f32_16x16x32_bf16 v[82:85], v[168:171], v[198:201], v[82:85]
	v_mfma_f32_16x16x32_bf16 v[70:73], v[160:163], v[206:209], v[70:73]
	v_mfma_f32_16x16x32_bf16 v[66:69], v[168:171], v[206:209], v[66:69]
	v_mfma_f32_16x16x32_bf16 v[118:121], v[164:167], v[186:189], v[118:121]
	v_mfma_f32_16x16x32_bf16 v[114:117], v[178:181], v[186:189], v[114:117]
	v_mfma_f32_16x16x32_bf16 v[102:105], v[164:167], v[194:197], v[102:105]
	v_mfma_f32_16x16x32_bf16 v[98:101], v[178:181], v[194:197], v[98:101]
	v_mfma_f32_16x16x32_bf16 v[86:89], v[164:167], v[202:205], v[86:89]
	v_mfma_f32_16x16x32_bf16 v[82:85], v[178:181], v[202:205], v[82:85]
	v_mfma_f32_16x16x32_bf16 v[70:73], v[164:167], v[210:213], v[70:73]
	v_mfma_f32_16x16x32_bf16 v[66:69], v[178:181], v[210:213], v[66:69]
	s_setprio 0
	s_barrier
; #define WAIT_V(n) asm volatile("s_waitcnt vmcnt(" #n ")" ::: "memory")
; #define WAIT_L(n) asm volatile("s_waitcnt lgkmcnt(" #n ")" ::: "memory")
; #define BAR __builtin_amdgcn_s_barrier()
; #define SCHED __builtin_amdgcn_sched_barrier(0)
;     ...
;       LDA(At, 1, 1); STAGE(SBo(1, 0), b3, voffB); STAGE(SBo(1, 1), b3 + hstep, voffB); STAGE(SAo(1, 0), a3, voff);
;       WAIT_V(8); WAIT_L(0); BAR; MMA(1, 0, At, B0); MMA(1, 1, At, B1); BAR; SCHED;
;     }
;     if (wr == 0) BAR;
	s_add_i32 s4, s31, s8
	v_lshl_add_u64 v[214:215], v[214:215], 0, s[34:35]
	s_mov_b32 m0, s4
	ds_read_b128 v[182:185], v159 offset:49152
	ds_read_b128 v[186:189], v159 offset:50176
	ds_read_b128 v[190:193], v159 offset:51200
	ds_read_b128 v[194:197], v159 offset:52224
	ds_read_b128 v[198:201], v159 offset:53248
	ds_read_b128 v[202:205], v159 offset:54272
	ds_read_b128 v[206:209], v159 offset:55296
	ds_read_b128 v[210:213], v159 offset:56320
	global_load_lds_dwordx4 v[214:215], off
	s_add_i32 m0, s4, 0x2000
	s_add_u32 s2, s2, 0x40080
	v_lshl_add_u64 v[214:215], v[216:217], 0, s[34:35]
	s_addc_u32 s3, s3, 0
	s_add_i32 s4, s33, s8
	global_load_lds_dwordx4 v[214:215], off
	v_lshl_add_u64 v[214:215], s[2:3], 0, v[146:147]
	s_mov_b32 m0, s4
	s_nop 0
	global_load_lds_dwordx4 v[214:215], off
	v_lshl_add_u64 v[214:215], s[2:3], 0, v[142:143]
	s_add_i32 m0, s4, 0x2000
	s_nop 0
	global_load_lds_dwordx4 v[214:215], off
	v_lshl_add_u64 v[214:215], v[218:219], 0, s[34:35]
	s_mov_b32 m0, s15
	s_nop 0
	global_load_lds_dwordx4 v[214:215], off
	v_lshl_add_u64 v[214:215], v[220:221], 0, s[34:35]
	s_mov_b32 m0, s16
	s_nop 0
	global_load_lds_dwordx4 v[214:215], off
	s_waitcnt vmcnt(8)
	s_waitcnt lgkmcnt(0)
	s_barrier
	s_setprio 1
	s_waitcnt lgkmcnt(0)
	v_mfma_f32_16x16x32_bf16 v[62:65], v[130:133], v[182:185], v[62:65]
	v_mfma_f32_16x16x32_bf16 v[58:61], v[138:141], v[182:185], v[58:61]
	v_mfma_f32_16x16x32_bf16 v[46:49], v[130:133], v[190:193], v[46:49]
	v_mfma_f32_16x16x32_bf16 v[42:45], v[138:141], v[190:193], v[42:45]
	v_mfma_f32_16x16x32_bf16 v[30:33], v[130:133], v[198:201], v[30:33]
	v_mfma_f32_16x16x32_bf16 v[26:29], v[138:141], v[198:201], v[26:29]
	v_mfma_f32_16x16x32_bf16 v[14:17], v[130:133], v[206:209], v[14:17]
	v_mfma_f32_16x16x32_bf16 v[10:13], v[138:141], v[206:209], v[10:13]
	v_mfma_f32_16x16x32_bf16 v[62:65], v[134:137], v[186:189], v[62:65]
	v_mfma_f32_16x16x32_bf16 v[58:61], v[154:157], v[186:189], v[58:61]
	v_mfma_f32_16x16x32_bf16 v[46:49], v[134:137], v[194:197], v[46:49]
	v_mfma_f32_16x16x32_bf16 v[42:45], v[154:157], v[194:197], v[42:45]
	v_mfma_f32_16x16x32_bf16 v[30:33], v[134:137], v[202:205], v[30:33]
	v_mfma_f32_16x16x32_bf16 v[26:29], v[154:157], v[202:205], v[26:29]
	v_mfma_f32_16x16x32_bf16 v[14:17], v[134:137], v[210:213], v[14:17]
	v_mfma_f32_16x16x32_bf16 v[10:13], v[154:157], v[210:213], v[10:13]
	s_setprio 0
	s_setprio 1
	v_mfma_f32_16x16x32_bf16 v[54:57], v[160:163], v[182:185], v[54:57]
	v_mfma_f32_16x16x32_bf16 v[50:53], v[168:171], v[182:185], v[50:53]
	v_mfma_f32_16x16x32_bf16 v[38:41], v[160:163], v[190:193], v[38:41]
	v_mfma_f32_16x16x32_bf16 v[34:37], v[168:171], v[190:193], v[34:37]
	v_mfma_f32_16x16x32_bf16 v[22:25], v[160:163], v[198:201], v[22:25]
	v_mfma_f32_16x16x32_bf16 v[18:21], v[168:171], v[198:201], v[18:21]
	v_mfma_f32_16x16x32_bf16 v[6:9], v[160:163], v[206:209], v[6:9]
	v_mfma_f32_16x16x32_bf16 v[2:5], v[168:171], v[206:209], v[2:5]
	v_mfma_f32_16x16x32_bf16 v[54:57], v[164:167], v[186:189], v[54:57]
	v_mfma_f32_16x16x32_bf16 v[50:53], v[178:181], v[186:189], v[50:53]
	v_mfma_f32_16x16x32_bf16 v[38:41], v[164:167], v[194:197], v[38:41]
	v_mfma_f32_16x16x32_bf16 v[34:37], v[178:181], v[194:197], v[34:37]
	v_mfma_f32_16x16x32_bf16 v[22:25], v[164:167], v[202:205], v[22:25]
	v_mfma_f32_16x16x32_bf16 v[18:21], v[178:181], v[202:205], v[18:21]
	v_mfma_f32_16x16x32_bf16 v[6:9], v[164:167], v[210:213], v[6:9]
	v_mfma_f32_16x16x32_bf16 v[2:5], v[178:181], v[210:213], v[2:5]
	s_setprio 0
	s_barrier
	s_add_i32 s30, s30, 2
	s_add_u32 s0, s0, 0x100
	s_addc_u32 s1, s1, 0
	s_add_u32 s28, s28, 0x100
	s_addc_u32 s29, s29, 0
	s_cmp_gt_u32 s30, 13
	s_cbranch_scc0 .LBB0_152
	s_and_b64 vcc, exec, s[46:47]
	s_cbranch_vccz .LBB0_155
	s_barrier

; DI float siluf(float x) { return x * __builtin_amdgcn_rcpf(1.f + __expf(-x)); }
; template <int EPI>
; DI void gemm_epilogue(const Params& p, int layer, f32x4 (&acc)[2][2][4][2], int brow, int bcol, int pn, int wr, int wc,
;                       int fr, int fq, char* smem, int ksplit = -1) {
;     ...
;       const float sc = (pn == 0 || pn == 6 || pn == 11) ? 0.125f : 1.f;
;       const bool dosilu = (pn == 0);
; #pragma unroll
;       for (int ai = 0; ai < 2; ++ai)
; #pragma unroll
;         for (int m = 0; m < 4; ++m) {
;           __builtin_amdgcn_sched_barrier(0);
;           const int row = brow + ai * 128 + wr * 64 + m * 16 + fr;
; #pragma unroll
;           for (int bj = 0; bj < 2; ++bj) {
;             u32x4 o;
; #pragma unroll
;             for (int n = 0; n < 2; ++n) {
;               f32x4 v = acc[ai][bj][m][n];
;               if (dosilu) {
; #pragma unroll
;                 for (int j = 0; j < 4; ++j) v[j] = siluf(v[j]);
;               }
;               v = v * sc;
;               o[2 * n] = pk_bf16(v[0], v[1]);
;               o[2 * n + 1] = pk_bf16(v[2], v[3]);
;             }
;             *(u32x4*)(Z + (size_t)row * ZW + bcol + bj * 128 + wc * 32 + fq * 8) = o;
.LBB0_168:
	s_add_i32 s0, s22, s14
	v_or_b32_e32 v162, s0, v160
	s_lshl_b32 s0, s25, 1
	s_add_u32 s0, s19, s0
	s_addc_u32 s1, s20, 0
	v_lshlrev_b32_e32 v0, 4, v161
	v_lshl_add_u64 v[138:139], s[0:1], 0, v[0:1]
	v_mad_i64_i32 v[140:141], s[0:1], v162, s79, v[138:139]
	s_waitcnt vmcnt(0)
	s_mov_b32 s100, 1
	ds_bpermute_b32 v130, v200, v130
	ds_bpermute_b32 v131, v200, v131
	ds_bpermute_b32 v132, v200, v132
	ds_bpermute_b32 v133, v200, v133
	s_waitcnt lgkmcnt(0)
	global_store_dwordx4 v[140:141], v[130:133], off
	v_cndmask_b32_e64 v0, 0, 1, s[4:5]
	v_cmp_ne_u32_e64 s[0:1], 1, v0
	v_mov_b64_e32 v[132:133], v[116:117]
	s_andn2_b64 vcc, exec, s[4:5]
	v_mov_b64_e32 v[130:131], v[114:115]
	s_cbranch_vccnz .LBB0_170
	v_mul_f32_e32 v0, 0xbfb8aa3b, v114
	v_exp_f32_e32 v0, v0
	v_mul_f32_e32 v130, 0xbfb8aa3b, v115
	v_mul_f32_e32 v131, 0xbfb8aa3b, v116
	v_exp_f32_e32 v132, v130
	v_add_f32_e32 v0, 1.0, v0
	v_rcp_f32_e32 v130, v0
	v_exp_f32_e32 v0, v131
	v_mul_f32_e32 v131, 0xbfb8aa3b, v117
	v_exp_f32_e32 v131, v131
	v_add_f32_e32 v156, 1.0, v132
	v_add_f32_e32 v0, 1.0, v0
	v_rcp_f32_e32 v132, v0
	v_add_f32_e32 v0, 1.0, v131
	v_rcp_f32_e32 v133, v0
	v_rcp_f32_e32 v131, v156
	v_pk_mul_f32 v[132:133], v[116:117], v[132:133]
	v_pk_mul_f32 v[130:131], v[114:115], v[130:131]

; DI float xsum32(float x) { auto r = __builtin_amdgcn_permlane32_swap(__float_as_uint(x), __float_as_uint(x), false, false); return __uint_as_float(r[0]) + __uint_as_float(r[1]); }
; DI float xsum16(float x) { auto r = __builtin_amdgcn_permlane16_swap(__float_as_uint(x), __float_as_uint(x), false, false); return __uint_as_float(r[0]) + __uint_as_float(r[1]); }
; template <int EPI>
; DI void gemm_epilogue(const Params& p, int layer, f32x4 (&acc)[2][2][4][2], int brow, int bcol, int pn, int wr, int wc,
;                       int fr, int fq, char* smem, int ksplit = -1) {
;     ...
;       float* xch = (float*)smem;
; #pragma unroll
;       for (int ai = 0; ai < 2; ++ai)
; #pragma unroll
;         for (int m = 0; m < 4; ++m)
; #pragma unroll
;           for (int bj = 0; bj < 2; ++bj) {
;             float s = 0.f;
; #pragma unroll
;             for (int n = 0; n < 2; ++n)
; #pragma unroll
;               for (int j = 0; j < 4; ++j) s += acc[ai][bj][m][n][j] * acc[ai][bj][m][n][j];
;             s = xsum16(s);
;             s = xsum32(s);
;             if (fq == 0) xch[(ai * 128 + wr * 64 + m * 16 + fr) * 8 + bj * 4 + wc] = s;
;           }
;       __syncthreads();
.LBB0_227:
	s_and_b64 vcc, exec, s[0:1]
	s_cbranch_vccz .LBB0_373
	s_waitcnt vmcnt(0)
	s_mov_b32 s100, 1
	v_mul_f32_e32 v130, v127, v127
	v_fmac_f32_e32 v130, v126, v126
	v_fmac_f32_e32 v130, v128, v128
	v_fmac_f32_e32 v130, v129, v129
	v_fmac_f32_e32 v130, v122, v122
	v_fmac_f32_e32 v130, v123, v123
	v_fmac_f32_e32 v130, v124, v124
	v_fmac_f32_e32 v130, v125, v125
	v_mov_b32_e32 v131, v130
	s_nop 1
	v_permlane16_swap_b32_e32 v130, v131
	v_add_f32_e32 v130, v130, v131
	v_lshlrev_b32_e32 v0, 5, v160
	v_mov_b32_e32 v131, v130
	v_cmp_eq_u32_e32 vcc, 0, v161
	s_nop 0
	v_permlane32_swap_b32_e32 v130, v131
	v_add_u32_e32 v0, s17, v0
	s_and_saveexec_b64 s[0:1], vcc
	v_add_f32_e32 v130, v130, v131
	ds_write_b32 v0, v130
	s_or_b64 exec, exec, s[0:1]
	v_mul_f32_e32 v130, v119, v119
	v_fmac_f32_e32 v130, v118, v118
	v_fmac_f32_e32 v130, v120, v120
	v_fmac_f32_e32 v130, v121, v121
	v_fmac_f32_e32 v130, v114, v114
	v_fmac_f32_e32 v130, v115, v115
	v_fmac_f32_e32 v130, v116, v116
	v_fmac_f32_e32 v130, v117, v117
	v_mov_b32_e32 v131, v130
	s_nop 1
	v_permlane16_swap_b32_e32 v130, v131
	v_add_f32_e32 v130, v130, v131
	v_mov_b32_e32 v131, v130
	s_nop 1
	v_permlane32_swap_b32_e32 v130, v131
	s_and_saveexec_b64 s[0:1], vcc
	v_add_f32_e32 v130, v130, v131
	ds_write_b32 v0, v130 offset:16
	s_or_b64 exec, exec, s[0:1]
	v_mul_f32_e32 v130, v111, v111
	v_fmac_f32_e32 v130, v110, v110
	v_fmac_f32_e32 v130, v112, v112
	v_fmac_f32_e32 v130, v113, v113
	v_fmac_f32_e32 v130, v106, v106
	v_fmac_f32_e32 v130, v107, v107
	v_fmac_f32_e32 v130, v108, v108
	v_fmac_f32_e32 v130, v109, v109
	v_mov_b32_e32 v131, v130
	s_nop 1
	v_permlane16_swap_b32_e32 v130, v131
	v_add_f32_e32 v130, v130, v131
	v_mov_b32_e32 v131, v130
	s_nop 1
	v_permlane32_swap_b32_e32 v130, v131
	s_and_saveexec_b64 s[0:1], vcc
	v_add_f32_e32 v130, v130, v131
	ds_write_b32 v0, v130 offset:512
	s_or_b64 exec, exec, s[0:1]
	v_mul_f32_e32 v130, v103, v103
	v_fmac_f32_e32 v130, v102, v102
	v_fmac_f32_e32 v130, v104, v104
	v_fmac_f32_e32 v130, v105, v105
	v_fmac_f32_e32 v130, v98, v98
	v_fmac_f32_e32 v130, v99, v99
	v_fmac_f32_e32 v130, v100, v100
	v_fmac_f32_e32 v130, v101, v101
	v_mov_b32_e32 v131, v130
	s_nop 1
	v_permlane16_swap_b32_e32 v130, v131
	v_add_f32_e32 v130, v130, v131
	v_mov_b32_e32 v131, v130
	s_nop 1
	v_permlane32_swap_b32_e32 v130, v131
	s_and_saveexec_b64 s[0:1], vcc
	v_add_f32_e32 v130, v130, v131
	ds_write_b32 v0, v130 offset:528
	s_or_b64 exec, exec, s[0:1]
	v_mul_f32_e32 v130, v95, v95
	v_fmac_f32_e32 v130, v94, v94
	v_fmac_f32_e32 v130, v96, v96
	v_fmac_f32_e32 v130, v97, v97
	v_fmac_f32_e32 v130, v90, v90
	v_fmac_f32_e32 v130, v91, v91
	v_fmac_f32_e32 v130, v92, v92
	v_fmac_f32_e32 v130, v93, v93
	v_mov_b32_e32 v131, v130
	s_nop 1
	v_permlane16_swap_b32_e32 v130, v131
	v_add_f32_e32 v130, v130, v131
	v_mov_b32_e32 v131, v130
	s_nop 1
	v_permlane32_swap_b32_e32 v130, v131
	s_and_saveexec_b64 s[0:1], vcc
	v_add_f32_e32 v130, v130, v131
	ds_write_b32 v0, v130 offset:1024
	s_or_b64 exec, exec, s[0:1]
	v_mul_f32_e32 v130, v87, v87
	v_fmac_f32_e32 v130, v86, v86
	v_fmac_f32_e32 v130, v88, v88
	v_fmac_f32_e32 v130, v89, v89
	v_fmac_f32_e32 v130, v82, v82
	v_fmac_f32_e32 v130, v83, v83
	v_fmac_f32_e32 v130, v84, v84
	v_fmac_f32_e32 v130, v85, v85
	v_mov_b32_e32 v131, v130
	s_nop 1
	v_permlane16_swap_b32_e32 v130, v131
	v_add_f32_e32 v130, v130, v131
	v_mov_b32_e32 v131, v130
	s_nop 1
	v_permlane32_swap_b32_e32 v130, v131
	s_and_saveexec_b64 s[0:1], vcc
	v_add_f32_e32 v130, v130, v131
	ds_write_b32 v0, v130 offset:1040
	s_or_b64 exec, exec, s[0:1]
	v_mul_f32_e32 v130, v79, v79
	v_fmac_f32_e32 v130, v78, v78
	v_fmac_f32_e32 v130, v80, v80
	v_fmac_f32_e32 v130, v81, v81
	v_fmac_f32_e32 v130, v74, v74
	v_fmac_f32_e32 v130, v75, v75
	v_fmac_f32_e32 v130, v76, v76
	v_fmac_f32_e32 v130, v77, v77
	v_mov_b32_e32 v131, v130
	s_nop 1
	v_permlane16_swap_b32_e32 v130, v131
	v_add_f32_e32 v130, v130, v131
	v_mov_b32_e32 v131, v130
	s_nop 1
	v_permlane32_swap_b32_e32 v130, v131
	s_and_saveexec_b64 s[0:1], vcc
	v_add_f32_e32 v130, v130, v131
	ds_write_b32 v0, v130 offset:1536
	s_or_b64 exec, exec, s[0:1]
	v_mul_f32_e32 v130, v71, v71
	v_fmac_f32_e32 v130, v70, v70
	v_fmac_f32_e32 v130, v72, v72
	v_fmac_f32_e32 v130, v73, v73
	v_fmac_f32_e32 v130, v66, v66
	v_fmac_f32_e32 v130, v67, v67
	v_fmac_f32_e32 v130, v68, v68
	v_fmac_f32_e32 v130, v69, v69
	v_mov_b32_e32 v131, v130
	s_nop 1
	v_permlane16_swap_b32_e32 v130, v131
	v_add_f32_e32 v130, v130, v131
	v_mov_b32_e32 v131, v130
	s_nop 1
	v_permlane32_swap_b32_e32 v130, v131
	s_and_saveexec_b64 s[0:1], vcc
	v_add_f32_e32 v130, v130, v131
	ds_write_b32 v0, v130 offset:1552
	s_or_b64 exec, exec, s[0:1]
	v_mul_f32_e32 v130, v63, v63
	v_fmac_f32_e32 v130, v62, v62
	v_fmac_f32_e32 v130, v64, v64
	v_fmac_f32_e32 v130, v65, v65
	v_fmac_f32_e32 v130, v58, v58
	v_fmac_f32_e32 v130, v59, v59
	v_fmac_f32_e32 v130, v60, v60
	v_fmac_f32_e32 v130, v61, v61
	v_mov_b32_e32 v131, v130
	s_nop 1
	v_permlane16_swap_b32_e32 v130, v131
	v_add_f32_e32 v130, v130, v131
	v_mov_b32_e32 v131, v130
	s_nop 1
	v_permlane32_swap_b32_e32 v130, v131
	s_and_saveexec_b64 s[0:1], vcc
	v_add_f32_e32 v130, v130, v131
	ds_write_b32 v0, v130 offset:4096
	s_or_b64 exec, exec, s[0:1]
	v_mul_f32_e32 v130, v55, v55
	v_fmac_f32_e32 v130, v54, v54
	v_fmac_f32_e32 v130, v56, v56
	v_fmac_f32_e32 v130, v57, v57
	v_fmac_f32_e32 v130, v50, v50
	v_fmac_f32_e32 v130, v51, v51
	v_fmac_f32_e32 v130, v52, v52
	v_fmac_f32_e32 v130, v53, v53
	v_mov_b32_e32 v131, v130
	s_nop 1
	v_permlane16_swap_b32_e32 v130, v131
	v_add_f32_e32 v130, v130, v131
	v_mov_b32_e32 v131, v130
	s_nop 1
	v_permlane32_swap_b32_e32 v130, v131
; DI float xsum32(float x) { auto r = __builtin_amdgcn_permlane32_swap(__float_as_uint(x), __float_as_uint(x), false, false); return __uint_as_float(r[0]) + __uint_as_float(r[1]); }
; template <int EPI>
; DI void gemm_epilogue(const Params& p, int layer, f32x4 (&acc)[2][2][4][2], int brow, int bcol, int pn, int wr, int wc,
;                       int fr, int fq, char* smem, int ksplit = -1) {
;     ...
;             float s = 0.f;
; #pragma unroll
;             for (int n = 0; n < 2; ++n)
; #pragma unroll
;               for (int j = 0; j < 4; ++j) s += acc[ai][bj][m][n][j] * acc[ai][bj][m][n][j];
;             s = xsum16(s);
;             s = xsum32(s);
;             if (fq == 0) xch[(ai * 128 + wr * 64 + m * 16 + fr) * 8 + bj * 4 + wc] = s;
;           }
;       __syncthreads();
;       const float* gq = (pn == 9 ? p.qn_g : p.kn_g) + layer * 64;
; #pragma unroll
;       for (int ai = 0; ai < 2; ++ai)
; #pragma unroll
;         for (int m = 0; m < 4; ++m) {
;           __builtin_amdgcn_sched_barrier(0);
;           const int rl = ai * 128 + wr * 64 + m * 16 + fr;
;           const int row = brow + rl;
;           const int spos = row & (SEQ - 1);
; #pragma unroll
;           for (int bj = 0; bj < 2; ++bj) {
;             const bool normed = (pn == 9) || (bj == 0);
;             float rs = 1.f;
;             if (normed) {
;               float tot = xch[rl * 8 + bj * 4 + wc] + xch[rl * 8 + bj * 4 + (wc ^ 1)];
;               rs = __builtin_amdgcn_rsqf(tot * (1.f / 64.f) + EPSN);
;             }
;             u32x4 o;
; #pragma unroll
;             for (int n = 0; n < 2; ++n) {
;               const int cih = (wc & 1) * 32 + fq * 8 + n * 4;
;               f32x4 v = acc[ai][bj][m][n];
;               if (normed) {
;                 f32x4 g = *(const f32x4*)(gq + cih);
;                 v = v * rs * g;
;                 if (latent) {
;                   const float2 cs = *(const float2*)(p.ropec + spos * 32 + (cih >> 1));
;                   const float2 sn = *(const float2*)(p.ropes + spos * 32 + (cih >> 1));
;                   f32x4 r;
;                   r[0] = v[0] * cs.x - v[1] * sn.x;
;                   r[1] = v[0] * sn.x + v[1] * cs.x;
;                   r[2] = v[2] * cs.y - v[3] * sn.y;
;                   r[3] = v[2] * sn.y + v[3] * cs.y;
	s_and_saveexec_b64 s[0:1], vcc
	v_add_f32_e32 v130, v130, v131
	ds_write_b32 v0, v130 offset:4112
	s_or_b64 exec, exec, s[0:1]
	v_mul_f32_e32 v130, v47, v47
	v_fmac_f32_e32 v130, v46, v46
	v_fmac_f32_e32 v130, v48, v48
	v_fmac_f32_e32 v130, v49, v49
	v_fmac_f32_e32 v130, v42, v42
	v_fmac_f32_e32 v130, v43, v43
	v_fmac_f32_e32 v130, v44, v44
	v_fmac_f32_e32 v130, v45, v45
	v_mov_b32_e32 v131, v130
	s_nop 1
	v_permlane16_swap_b32_e32 v130, v131
	v_add_f32_e32 v130, v130, v131
	v_mov_b32_e32 v131, v130
	s_nop 1
	v_permlane32_swap_b32_e32 v130, v131
	s_and_saveexec_b64 s[0:1], vcc
	v_add_f32_e32 v130, v130, v131
	ds_write_b32 v0, v130 offset:4608
	s_or_b64 exec, exec, s[0:1]
	v_mul_f32_e32 v130, v39, v39
	v_fmac_f32_e32 v130, v38, v38
	v_fmac_f32_e32 v130, v40, v40
	v_fmac_f32_e32 v130, v41, v41
	v_fmac_f32_e32 v130, v34, v34
	v_fmac_f32_e32 v130, v35, v35
	v_fmac_f32_e32 v130, v36, v36
	v_fmac_f32_e32 v130, v37, v37
	v_mov_b32_e32 v131, v130
	s_nop 1
	v_permlane16_swap_b32_e32 v130, v131
	v_add_f32_e32 v130, v130, v131
	v_mov_b32_e32 v131, v130
	s_nop 1
	v_permlane32_swap_b32_e32 v130, v131
	s_and_saveexec_b64 s[0:1], vcc
	v_add_f32_e32 v130, v130, v131
	ds_write_b32 v0, v130 offset:4624
	s_or_b64 exec, exec, s[0:1]
	v_mul_f32_e32 v130, v31, v31
	v_fmac_f32_e32 v130, v30, v30
	v_fmac_f32_e32 v130, v32, v32
	v_fmac_f32_e32 v130, v33, v33
	v_fmac_f32_e32 v130, v26, v26
	v_fmac_f32_e32 v130, v27, v27
	v_fmac_f32_e32 v130, v28, v28
	v_fmac_f32_e32 v130, v29, v29
	v_mov_b32_e32 v131, v130
	s_nop 1
	v_permlane16_swap_b32_e32 v130, v131
	v_add_f32_e32 v130, v130, v131
	v_mov_b32_e32 v131, v130
	s_nop 1
	v_permlane32_swap_b32_e32 v130, v131
	s_and_saveexec_b64 s[0:1], vcc
	v_add_f32_e32 v130, v130, v131
	ds_write_b32 v0, v130 offset:5120
	s_or_b64 exec, exec, s[0:1]
	v_mul_f32_e32 v130, v23, v23
	v_fmac_f32_e32 v130, v22, v22
	v_fmac_f32_e32 v130, v24, v24
	v_fmac_f32_e32 v130, v25, v25
	v_fmac_f32_e32 v130, v18, v18
	v_fmac_f32_e32 v130, v19, v19
	v_fmac_f32_e32 v130, v20, v20
	v_fmac_f32_e32 v130, v21, v21
	v_mov_b32_e32 v131, v130
	s_nop 1
	v_permlane16_swap_b32_e32 v130, v131
	v_add_f32_e32 v130, v130, v131
	v_mov_b32_e32 v131, v130
	s_nop 1
	v_permlane32_swap_b32_e32 v130, v131
	s_and_saveexec_b64 s[0:1], vcc
	v_add_f32_e32 v130, v130, v131
	ds_write_b32 v0, v130 offset:5136
	s_or_b64 exec, exec, s[0:1]
	v_mul_f32_e32 v130, v15, v15
	v_fmac_f32_e32 v130, v14, v14
	v_fmac_f32_e32 v130, v16, v16
	v_fmac_f32_e32 v130, v17, v17
	v_fmac_f32_e32 v130, v10, v10
	v_fmac_f32_e32 v130, v11, v11
	v_fmac_f32_e32 v130, v12, v12
	v_fmac_f32_e32 v130, v13, v13
	v_mov_b32_e32 v131, v130
	s_nop 1
	v_permlane16_swap_b32_e32 v130, v131
	v_add_f32_e32 v130, v130, v131
	v_mov_b32_e32 v131, v130
	s_nop 1
	v_permlane32_swap_b32_e32 v130, v131
	s_and_saveexec_b64 s[0:1], vcc
	v_add_f32_e32 v130, v130, v131
	ds_write_b32 v0, v130 offset:5632
	s_or_b64 exec, exec, s[0:1]
	v_mul_f32_e32 v130, v7, v7
	v_fmac_f32_e32 v130, v6, v6
	v_fmac_f32_e32 v130, v8, v8
	v_fmac_f32_e32 v130, v9, v9
	v_fmac_f32_e32 v130, v2, v2
	v_fmac_f32_e32 v130, v3, v3
	v_fmac_f32_e32 v130, v4, v4
	v_fmac_f32_e32 v130, v5, v5
	v_mov_b32_e32 v131, v130
	s_nop 1
	v_permlane16_swap_b32_e32 v130, v131
	v_add_f32_e32 v130, v130, v131
	v_mov_b32_e32 v131, v130
	s_nop 1
	v_permlane32_swap_b32_e32 v130, v131
	s_and_saveexec_b64 s[0:1], vcc
	v_add_f32_e32 v130, v130, v131
	ds_write_b32 v0, v130 offset:5648
	s_or_b64 exec, exec, s[0:1]
	s_cmpk_lt_u32 s23, 0x80
	s_cselect_b64 s[2:3], -1, 0
	s_cmp_eq_u32 s24, 9
	s_cselect_b64 s[0:1], -1, 0
	s_and_b64 s[4:5], s[0:1], exec
	v_readlane_b32 s60, v252, 32
	v_readlane_b32 s4, v255, 1
	v_readlane_b32 s70, v252, 42
	v_readlane_b32 s71, v252, 43
	v_readlane_b32 s72, v252, 44
	v_readlane_b32 s73, v252, 45
	v_readlane_b32 s5, v255, 2
	s_cselect_b32 s24, s71, s73
	s_cselect_b32 s26, s70, s72
	s_lshl_b64 s[4:5], s[4:5], 2
	s_add_u32 s4, s26, s4
	v_lshlrev_b32_e32 v156, 3, v161
	s_addc_u32 s5, s24, s5
	s_add_i32 s24, 0, 0x20000
	v_or_b32_e32 v154, s14, v160
	v_or_b32_e32 v140, s18, v156
	v_readlane_b32 s61, v252, 33
	v_readlane_b32 s62, v252, 34
	v_readlane_b32 s63, v252, 35
	v_readlane_b32 s64, v252, 36
	v_readlane_b32 s65, v252, 37
	v_readlane_b32 s66, v252, 38
	v_readlane_b32 s67, v252, 39
	v_readlane_b32 s68, v252, 40
	v_readlane_b32 s69, v252, 41
	v_readlane_b32 s74, v252, 46
	v_readlane_b32 s75, v252, 47
	s_cmpk_gt_u32 s23, 0x7f
	s_waitcnt vmcnt(0) lgkmcnt(0)
	s_barrier
	v_add_u32_e32 v155, s22, v154
	v_lshlrev_b32_e32 v0, 7, v155
	v_readlane_b32 s60, v254, 45
	v_and_b32_e32 v0, 0x3e780, v0
	v_readlane_b32 s66, v254, 51
	v_readlane_b32 s67, v254, 52
	v_readlane_b32 s68, v254, 53
	v_readlane_b32 s69, v254, 54
	v_lshl_add_u64 v[132:133], s[66:67], 0, v[0:1]
	v_lshlrev_b32_e32 v134, 3, v154
	v_lshl_add_u64 v[130:131], s[68:69], 0, v[0:1]
	v_lshlrev_b32_e32 v182, 1, v140
	v_mov_b32_e32 v183, 0
	v_lshl_add_u64 v[184:185], v[132:133], 0, v[182:183]
	global_load_dwordx4 v[186:189], v[184:185], off
	v_lshl_add_u64 v[184:185], v[130:131], 0, v[182:183]
	global_load_dwordx4 v[190:193], v[184:185], off
	v_lshlrev_b32_e32 v0, 2, v140
	global_load_dwordx4 v[162:165], v0, s[4:5]
	global_load_dwordx4 v[168:171], v0, s[4:5]
	global_load_dwordx4 v[178:181], v0, s[4:5] offset:16
	v_lshlrev_b32_e32 v182, 1, v140
	v_mov_b32_e32 v183, 0
	v_or_b32_e32 v160, s13, v134
	v_bitop3_b32 v134, v134, 1, s13 bitop3:0x36
	v_lshl_add_u32 v157, v160, 2, s24
	v_lshl_add_u32 v134, v134, 2, s24
	ds_read_b32 v135, v157
	ds_read_b32 v134, v134
	v_readlane_b32 s61, v254, 46
	v_readlane_b32 s62, v254, 47
	v_readlane_b32 s63, v254, 48
	v_readlane_b32 s64, v254, 49
	s_waitcnt lgkmcnt(0)
	v_add_f32_e32 v134, v135, v134
	v_fmamk_f32 v134, v134, 0x3c800000, v236
	v_rsq_f32_e32 v136, v134
	v_readlane_b32 s65, v254, 50
	v_readlane_b32 s70, v254, 55
	v_readlane_b32 s71, v254, 56
	v_pk_mul_f32 v[126:127], v[126:127], v[136:137] op_sel_hi:[1,0]
	v_pk_mul_f32 v[128:129], v[128:129], v[136:137] op_sel_hi:[1,0]
	v_readlane_b32 s72, v254, 57
	v_readlane_b32 s73, v254, 58
	v_readlane_b32 s74, v254, 59
	v_readlane_b32 s75, v254, 60
	s_waitcnt vmcnt(0)
	v_pk_mul_f32 v[134:135], v[164:165], v[128:129]
	v_pk_mul_f32 v[128:129], v[162:163], v[126:127]
	s_cbranch_scc1 .LBB0_262
	v_lshlrev_b32_e32 v126, 1, v140
	v_mov_b32_e32 v127, v1
	v_lshl_add_u64 v[138:139], v[132:133], 0, v[126:127]
	v_lshl_add_u64 v[126:127], v[130:131], 0, v[126:127]
	v_mov_b64_e32 v[126:127], v[190:191]
	v_pk_mul_f32 v[162:163], v[128:129], v[126:127] op_sel:[1,0] op_sel_hi:[0,0]
	v_mov_b64_e32 v[138:139], v[186:187]
	v_pk_mul_f32 v[164:165], v[128:129], v[138:139]
	v_pk_fma_f32 v[128:129], v[128:129], v[138:139], v[162:163] op_sel_hi:[1,0,1]
	v_mov_b32_e32 v126, v139
	v_mul_f32_e32 v128, v135, v127
	v_pk_fma_f32 v[166:167], v[134:135], v[126:127], v[128:129] op_sel_hi:[1,1,0] neg_lo:[0,0,1] neg_hi:[0,0,1]
	v_mov_b32_e32 v138, v127
	v_mul_f32_e32 v126, v135, v139
	v_pk_fma_f32 v[126:127], v[134:135], v[138:139], v[126:127] op_sel_hi:[1,1,0]
	v_sub_f32_e32 v128, v164, v162
	v_mov_b32_e32 v134, v166
	v_mov_b32_e32 v135, v126

;     ...
;   const int tid = opaque_tid(), wid = __builtin_amdgcn_readfirstlane(tid >> 6), lane = tid & 63, wr = wid >> 2, wc = wid & 3;
;   constexpr int nt = K / BK;
;   unsigned voff[2], voffB[2];
; #pragma unroll
;   for (int i = 0; i < 2; ++i) {
;     int r_, c_;
;     stage_rc(tid * 16 + i * 8192, r_, c_);
;     voff[i] = (unsigned)(r_ * K + c_) * 2u;
;     const int rho = r_ & 31, nn = rho >> 4, ii = rho & 15;
;     const int rb = (r_ & ~31) + 8 * (ii >> 2) + 4 * nn + (ii & 3);
;     voffB[i] = (unsigned)(rb * K + c_) * 2u;
;   }
;   const size_t kstep = (size_t)(BK * 2);
;   const size_t hstep = (size_t)HALF * K * 2;
;   const size_t tstep = 2 * hstep;
;   const unsigned ldsw = (unsigned)wid * 1024u;
;   const int aoff = lds_byte(wr * 64 + (lane & 15), (lane >> 4) * 8), boff = lds_byte(wc * 32 + (lane & 15), (lane >> 4) * 8);
;   auto unit = [&](int i, int& pm, int& pn, int& kq) -> bool {
;     const long L = (long)i * gridDim.x + blockIdx.x;
;     kq = -1;
;     if (SPLIT && L >= nwg) {
;       const int u = (int)(L - nwg);
;       if (u >= 16 * nMsplit) return false;
;       pm = nM + (u >> 4); pn = (u >> 2) & 3; kq = u & 3;
;       return true;
;     }
;     if (L >= nwg) return false;
;     int wgid = (int)L;
;     {
;       const int q = nwg / NXCD, r = nwg % NXCD, xcd = wgid % NXCD, off = wgid / NXCD;
;       wgid = (xcd < r ? xcd * (q + 1) : r * (q + 1) + (xcd - r) * q) + off;
;     }
;     const int nig = WGM * nN, gid = wgid / nig, fm = gid * WGM, gsz = min(nM - fm, WGM);
;     pm = fm + ((wgid % nig) % gsz);
;     pn = (wgid % nig) / gsz;
;     return true;
;   };
;   int pm, pn, kq, npm = 0, npn = 0, nkq = -1, ui = 0;
;   if (!unit(0, pm, pn, kq)) return;
;   const char* cA = (const char*)A + (size_t)pm * tstep + (kq > 0 ? (size_t)kq * (K / 4) * 2 : 0);
;   const char* cB = (const char*)Bt + (size_t)pn * tstep + (kq > 0 ? (size_t)kq * (K / 4) * 2 : 0);
;   f32x4 acc[2][2][4][2];
; #pragma unroll
;   for (int a = 0; a < 2; ++a)
; #pragma unroll
;     for (int b = 0; b < 2; ++b)
; #pragma unroll
;       for (int m = 0; m < 4; ++m)
; #pragma unroll
;         for (int n = 0; n < 2; ++n) acc[a][b][m][n] = (f32x4){0.f, 0.f, 0.f, 0.f};
;   bf16x8 At[4][2], B0[2][2], B1[2][2];
;   STAGE(SBo(0, 0), cB, voffB); STAGE(SBo(0, 1), cB + hstep, voffB); STAGE(SAo(0, 0), cA, voff); STAGE(SAo(0, 1), cA + hstep, voff);
;   if (wr == 1) BAR;
;   WAIT_V(2); BAR;
.LBB0_985:
	s_or_b64 exec, exec, s[0:1]
	v_readlane_b32 s0, v255, 6
	v_readlane_b32 s1, v255, 7
	s_lshl_b64 s[2:3], s[0:1], 23
	v_readlane_b32 s0, v254, 34
	v_readlane_b32 s1, v254, 35
	s_lshl_b32 s0, s28, 4
	v_writelane_b32 v254, s0, 34
	v_mov_b32_e32 v16, v234
	s_waitcnt lgkmcnt(0)
	s_barrier
	v_writelane_b32 v254, s1, 35
	s_mov_b32 s100, 0
	s_cmp_lt_u32 s57, s0
	s_nop 0
	v_readfirstlane_b32 s1, v16
	s_cbranch_scc0 .LBB0_1001
	v_lshlrev_b32_e32 v0, 4, v16
	s_waitcnt vmcnt(11)
	v_add_u32_e32 v2, 0x2000, v0
	v_ashrrev_i32_e32 v3, 31, v2
	v_lshrrev_b32_e32 v3, 22, v3
	v_add_u32_e32 v3, v2, v3
	v_ashrrev_i32_e32 v10, 10, v3
	v_readlane_b32 s4, v252, 0
	v_mul_i32_i24_e32 v3, 0x400, v10
	v_readlane_b32 s8, v252, 4
	v_readlane_b32 s9, v252, 5
	v_readlane_b32 s10, v252, 6
	v_readlane_b32 s11, v252, 7
	v_readlane_b32 s12, v252, 8
	v_readlane_b32 s13, v252, 9
	v_readlane_b32 s14, v252, 10
	v_readlane_b32 s15, v252, 11
	v_sub_u32_e32 v2, v2, v3
	v_readlane_b32 s16, v252, 12
	v_readlane_b32 s17, v252, 13
	v_readlane_b32 s18, v252, 14
	v_readlane_b32 s19, v252, 15
	s_mov_b64 s[8:9], s[12:13]
	v_lshrrev_b32_e32 v3, 4, v2
	s_mov_b64 s[10:11], s[14:15]
	s_mov_b64 s[12:13], s[16:17]
	s_mov_b64 s[14:15], s[18:19]
	v_readlane_b32 s0, v253, 40
	v_bitop3_b32 v2, v3, v2, 32 bitop3:0x6c
	s_add_u32 s26, s14, s2
	s_mul_i32 s0, s0, s28
	v_readlane_b32 s4, v253, 43
	v_ashrrev_i32_e32 v3, 31, v2
	s_addc_u32 s27, s15, s3
	s_add_i32 s0, s0, s4
	v_lshrrev_b32_e32 v3, 26, v3
	v_readlane_b32 s6, v252, 2
	s_lshr_b32 s4, s0, 4
	v_add_u32_e32 v3, v2, v3
	v_lshlrev_b32_e32 v4, 3, v10
	s_and_b32 s6, s4, 0x3fffff8
	v_ashrrev_i32_e32 v11, 6, v3
	v_and_b32_e32 v4, -16, v4
	s_sub_i32 s4, s28, s6
	v_add_u32_e32 v4, v11, v4
	s_min_i32 s9, s4, 8
	v_and_b32_e32 v5, 3, v11
	s_mov_b32 s4, 0x1fffe0
	s_waitcnt vmcnt(10)
	v_lshlrev_b32_e32 v6, 1, v4
	v_lshrrev_b32_e32 v7, 2, v4
	v_and_b32_e32 v3, 0xc0, v3
	v_and_or_b32 v5, v4, s4, v5
	v_and_b32_e32 v6, 24, v6
	v_and_b32_e32 v7, 4, v7
	v_sub_u32_e32 v2, v2, v3
	v_or3_b32 v5, v5, v6, v7
	v_lshlrev_b32_e32 v6, 5, v10
	v_ashrrev_i16_sdwa v2, v237, sext(v2) dst_sel:DWORD dst_unused:UNUSED_PAD src0_sel:DWORD src1_sel:BYTE_0
	v_and_b32_e32 v6, 32, v6
	v_bfe_i32 v12, v2, 0, 16
	v_add_lshl_u32 v2, v6, v12, 1
	s_waitcnt vmcnt(4)
	v_lshl_add_u32 v146, v5, 11, v2
	v_lshl_add_u32 v148, v4, 11, v2
	v_bfe_i32 v2, v16, 27, 1
	v_lshrrev_b32_e32 v2, 22, v2
	v_add_u32_e32 v2, v0, v2
	v_and_b32_e32 v2, 0xfffffc00, v2
	v_sub_u32_e32 v0, v0, v2
	v_lshrrev_b32_e32 v2, 4, v0
	v_bitop3_b32 v2, v2, v0, 32 bitop3:0x6c
	v_ashrrev_i32_e32 v0, 31, v0
	v_lshrrev_b32_e32 v0, 26, v0
	v_add_u32_e32 v0, v2, v0
	v_ashrrev_i32_e32 v13, 6, v0
	v_ashrrev_i32_e32 v0, 31, v16
	v_lshrrev_b32_e32 v0, 26, v0
	v_add_u32_e32 v0, v16, v0
	v_ashrrev_i32_e32 v14, 6, v0
	v_lshlrev_b32_e32 v0, 3, v14
	v_and_b32_e32 v0, -16, v0
	v_add_u32_e32 v3, v13, v0
	v_and_b32_e32 v0, 3, v13
	v_lshlrev_b32_e32 v4, 1, v3
	v_lshrrev_b32_e32 v5, 2, v3
	v_and_or_b32 v0, v3, s4, v0
	v_and_b32_e32 v4, 24, v4
	v_and_b32_e32 v5, 4, v5
	v_or3_b32 v0, v0, v4, v5
	v_mul_i32_i24_e32 v5, 64, v13
	v_sub_u32_e32 v2, v2, v5
	v_lshlrev_b32_e32 v4, 5, v14
	v_ashrrev_i16_sdwa v2, v237, sext(v2) dst_sel:DWORD dst_unused:UNUSED_PAD src0_sel:DWORD src1_sel:BYTE_0
	v_and_b32_e32 v4, 32, v4
	v_bfe_i32 v15, v2, 0, 16
	s_sext_i32_i8 s4, s9
	v_add_lshl_u32 v2, v4, v15, 1
	v_cvt_f32_i32_e32 v4, s4
	v_lshl_add_u32 v0, v0, 11, v2
	v_lshl_add_u32 v150, v3, 11, v2
	s_and_b32 s10, s0, 0x7f
	v_rcp_iflag_f32_e32 v2, v4
	v_cvt_f32_ubyte0_e32 v3, s10
	v_readlane_b32 s7, v252, 3
	v_readlane_b32 s5, v252, 1
	v_mul_f32_e32 v2, v3, v2
	v_trunc_f32_e32 v2, v2
	v_fma_f32 v3, -v2, v4, v3
	v_cvt_i32_f32_e32 v2, v2
	s_ashr_i32 s7, s1, 6
	s_ashr_i32 s0, s4, 30
	s_ashr_i32 s8, s1, 8
	s_lshl_b32 s29, s7, 10
	s_or_b32 s0, s0, 1
	v_cmp_ge_f32_e64 s[4:5], |v3|, |v4|
	s_and_b64 s[4:5], s[4:5], exec
	s_cselect_b32 s0, s0, 0
	v_readfirstlane_b32 s4, v2
	s_add_i32 s0, s4, s0
	s_mul_i32 s4, s0, s9
	s_sub_i32 s4, s10, s4
	s_and_b32 s4, s4, 0xff
	s_add_i32 s18, s6, s4
	v_readlane_b32 s4, v254, 34
	v_readlane_b32 s5, v254, 35
	s_mov_b32 s19, s5
	s_bfe_i64 s[10:11], s[0:1], 0x80000
	s_lshl_b64 s[4:5], s[18:19], 19
	s_lshl_b64 s[10:11], s[10:11], 19
	s_add_u32 s22, s26, s10
	s_addc_u32 s23, s27, s11
	s_add_i32 s19, s29, 0
	s_add_i32 m0, s19, 0x10000
	v_mov_b32_e32 v147, v1
	global_load_lds_dwordx4 v0, s[22:23]
	s_add_i32 m0, s19, 0x12000
	s_add_u32 s10, s22, 0x40000
	global_load_lds_dwordx4 v146, s[22:23]
	s_addc_u32 s11, s23, 0
	s_add_i32 m0, s19, 0x14000
	v_mov_b32_e32 v151, v1
	global_load_lds_dwordx4 v0, s[10:11]
	s_add_i32 m0, s19, 0x16000
	s_add_u32 s20, s76, s4
	s_addc_u32 s21, s77, s5
	s_add_i32 s30, s19, 0x2000
	global_load_lds_dwordx4 v146, s[10:11]
	s_mov_b32 m0, s19
	s_add_u32 s4, s20, 0x40000
	global_load_lds_dwordx4 v150, s[20:21]
	s_mov_b32 m0, s30
	s_addc_u32 s5, s21, 0
	s_add_i32 s31, s19, 0x4000
	global_load_lds_dwordx4 v148, s[20:21]
	s_mov_b32 m0, s31
	s_add_i32 s33, s19, 0x6000
	global_load_lds_dwordx4 v150, s[4:5]
	s_mov_b32 m0, s33
	v_mov_b32_e32 v149, v1
	global_load_lds_dwordx4 v148, s[4:5]
	s_cmp_eq_u32 s8, 1
	v_lshl_add_u64 v[8:9], s[22:23], 0, v[0:1]
	v_lshl_add_u64 v[6:7], s[22:23], 0, v[146:147]
	v_lshl_add_u64 v[2:3], s[20:21], 0, v[150:151]
	s_cselect_b64 s[4:5], -1, 0
	s_cmp_lg_u32 s8, 1
	v_lshl_add_u64 v[4:5], s[20:21], 0, v[148:149]
	s_cbranch_scc1 .LBB0_988
	s_barrier

; #define WAIT_V(n) asm volatile("s_waitcnt vmcnt(" #n ")" ::: "memory")
; #define WAIT_L(n) asm volatile("s_waitcnt lgkmcnt(" #n ")" ::: "memory")
; #define BAR __builtin_amdgcn_s_barrier()
; #define SCHED __builtin_amdgcn_sched_barrier(0)
;     ...
;       LDB(B0, 0, 0); LDB(B1, 0, 1); SCHED; LDA(At, 0, 0); STAGE(SAo(1, 1), a1 + hstep, voff);
;       WAIT_V(8); WAIT_L(0); BAR; MMA(0, 0, At, B0); MMA(0, 1, At, B1); BAR; SCHED;
;       LDA(At, 0, 1); STAGE(SBo(0, 0), b2, voffB); STAGE(SBo(0, 1), b2 + hstep, voffB); STAGE(SAo(0, 0), a2, voff);
;       WAIT_V(8); WAIT_L(0); BAR; MMA(1, 0, At, B0); MMA(1, 1, At, B1); BAR; SCHED;
.LBB0_994:
	s_add_u32 s22, s20, 0xfffc0080
	s_addc_u32 s23, s21, -1
	s_add_i32 s53, 0, 0x10000
	s_cmp_eq_u32 s52, 12
	s_cselect_b32 s25, s11, s23
	s_cselect_b32 s24, s48, s22
	s_cselect_b32 s23, s13, s51
	s_cselect_b32 s22, s49, s50
	s_add_i32 s56, 0, 0x14000
	v_add_u32_e32 v142, s53, v158
	v_add_u32_e32 v156, s56, v158
	ds_read_b128 v[130:133], v142
	ds_read_b128 v[134:137], v142 offset:1024
	ds_read_b128 v[138:141], v142 offset:2048
	ds_read_b128 v[142:145], v142 offset:3072
	ds_read_b128 v[160:163], v156
	ds_read_b128 v[164:167], v156 offset:1024
	ds_read_b128 v[168:171], v156 offset:2048
	ds_read_b128 v[178:181], v156 offset:3072
	v_lshl_add_u64 v[156:157], s[20:21], 0, v[152:153]
	s_add_i32 m0, s19, 0xc000
	ds_read_b128 v[182:185], v159
	ds_read_b128 v[186:189], v159 offset:1024
	ds_read_b128 v[190:193], v159 offset:2048
	ds_read_b128 v[194:197], v159 offset:3072
	ds_read_b128 v[198:201], v159 offset:4096
	ds_read_b128 v[202:205], v159 offset:5120
	ds_read_b128 v[206:209], v159 offset:6144
	ds_read_b128 v[210:213], v159 offset:7168
	global_load_lds_dwordx4 v[156:157], off
	v_lshl_add_u64 v[156:157], s[20:21], 0, v[154:155]
	s_add_i32 m0, s19, 0xe000
	s_nop 0
	global_load_lds_dwordx4 v[156:157], off
	s_cmp_lg_u32 s100, 0
	s_cbranch_scc1 .Lkp_m1_0
	s_waitcnt vmcnt(8)
.Lkp_m1_0:
	s_waitcnt lgkmcnt(0)
	s_barrier
	s_setprio 1
	s_waitcnt lgkmcnt(0)
	v_mfma_f32_16x16x32_bf16 v[126:129], v[130:133], v[182:185], v[126:129]
	v_mfma_f32_16x16x32_bf16 v[122:125], v[138:141], v[182:185], v[122:125]
	v_mfma_f32_16x16x32_bf16 v[110:113], v[130:133], v[190:193], v[110:113]
	v_mfma_f32_16x16x32_bf16 v[106:109], v[138:141], v[190:193], v[106:109]
	v_mfma_f32_16x16x32_bf16 v[94:97], v[130:133], v[198:201], v[94:97]
	v_mfma_f32_16x16x32_bf16 v[90:93], v[138:141], v[198:201], v[90:93]
	v_mfma_f32_16x16x32_bf16 v[78:81], v[130:133], v[206:209], v[78:81]
	v_mfma_f32_16x16x32_bf16 v[74:77], v[138:141], v[206:209], v[74:77]
	v_mfma_f32_16x16x32_bf16 v[126:129], v[134:137], v[186:189], v[126:129]
	v_mfma_f32_16x16x32_bf16 v[122:125], v[142:145], v[186:189], v[122:125]
	v_mfma_f32_16x16x32_bf16 v[110:113], v[134:137], v[194:197], v[110:113]
	v_mfma_f32_16x16x32_bf16 v[106:109], v[142:145], v[194:197], v[106:109]
	v_mfma_f32_16x16x32_bf16 v[94:97], v[134:137], v[202:205], v[94:97]
	v_mfma_f32_16x16x32_bf16 v[90:93], v[142:145], v[202:205], v[90:93]
	v_mfma_f32_16x16x32_bf16 v[78:81], v[134:137], v[210:213], v[78:81]
	v_mfma_f32_16x16x32_bf16 v[74:77], v[142:145], v[210:213], v[74:77]
	s_setprio 0
	s_setprio 1
	v_mfma_f32_16x16x32_bf16 v[118:121], v[160:163], v[182:185], v[118:121]
	v_mfma_f32_16x16x32_bf16 v[114:117], v[168:171], v[182:185], v[114:117]
	v_mfma_f32_16x16x32_bf16 v[102:105], v[160:163], v[190:193], v[102:105]
	v_mfma_f32_16x16x32_bf16 v[98:101], v[168:171], v[190:193], v[98:101]
	v_mfma_f32_16x16x32_bf16 v[86:89], v[160:163], v[198:201], v[86:89]
	v_mfma_f32_16x16x32_bf16 v[82:85], v[168:171], v[198:201], v[82:85]
	v_mfma_f32_16x16x32_bf16 v[70:73], v[160:163], v[206:209], v[70:73]
	v_mfma_f32_16x16x32_bf16 v[66:69], v[168:171], v[206:209], v[66:69]
	v_mfma_f32_16x16x32_bf16 v[118:121], v[164:167], v[186:189], v[118:121]
	v_mfma_f32_16x16x32_bf16 v[114:117], v[178:181], v[186:189], v[114:117]
	v_mfma_f32_16x16x32_bf16 v[102:105], v[164:167], v[194:197], v[102:105]
	v_mfma_f32_16x16x32_bf16 v[98:101], v[178:181], v[194:197], v[98:101]
	v_mfma_f32_16x16x32_bf16 v[86:89], v[164:167], v[202:205], v[86:89]
	v_mfma_f32_16x16x32_bf16 v[82:85], v[178:181], v[202:205], v[82:85]
	v_mfma_f32_16x16x32_bf16 v[70:73], v[164:167], v[210:213], v[70:73]
	v_mfma_f32_16x16x32_bf16 v[66:69], v[178:181], v[210:213], v[66:69]
	s_setprio 0
	s_barrier
	s_add_i32 s53, s53, s29
	v_lshl_add_u64 v[156:157], s[22:23], 0, v[0:1]
	s_mov_b32 m0, s53
	ds_read_b128 v[182:185], v159 offset:16384
	ds_read_b128 v[186:189], v159 offset:17408
	ds_read_b128 v[190:193], v159 offset:18432
	ds_read_b128 v[194:197], v159 offset:19456
	ds_read_b128 v[198:201], v159 offset:20480
	ds_read_b128 v[202:205], v159 offset:21504
	ds_read_b128 v[206:209], v159 offset:22528
	ds_read_b128 v[210:213], v159 offset:23552
	global_load_lds_dwordx4 v[156:157], off
	s_add_i32 m0, s53, 0x2000
	s_add_u32 s54, s22, 0x40000
	v_lshl_add_u64 v[214:215], s[22:23], 0, v[146:147]
	s_addc_u32 s55, s23, 0
	s_add_i32 s53, s56, s29
	global_load_lds_dwordx4 v[214:215], off
	v_lshl_add_u64 v[216:217], s[54:55], 0, v[0:1]
	s_mov_b32 m0, s53
	v_lshl_add_u64 v[218:219], s[24:25], 0, v[148:149]
	global_load_lds_dwordx4 v[216:217], off
	v_lshl_add_u64 v[216:217], s[54:55], 0, v[146:147]
	s_add_i32 m0, s53, 0x2000
	s_nop 0
	global_load_lds_dwordx4 v[216:217], off
	v_lshl_add_u64 v[216:217], s[24:25], 0, v[150:151]
	s_mov_b32 m0, s19
	s_nop 0
	global_load_lds_dwordx4 v[216:217], off
	s_mov_b32 m0, s30
	s_nop 0
	global_load_lds_dwordx4 v[218:219], off
	s_cmp_lg_u32 s100, 0
	s_cbranch_scc1 .Lkp_m1_1
	s_waitcnt vmcnt(8)
; #define WAIT_V(n) asm volatile("s_waitcnt vmcnt(" #n ")" ::: "memory")
; #define WAIT_L(n) asm volatile("s_waitcnt lgkmcnt(" #n ")" ::: "memory")
; #define BAR __builtin_amdgcn_s_barrier()
; #define SCHED __builtin_amdgcn_sched_barrier(0)
;     ...
;       WAIT_V(8); WAIT_L(0); BAR; MMA(0, 0, At, B0); MMA(0, 1, At, B1); BAR; SCHED;
;       LDA(At, 0, 1); STAGE(SBo(0, 0), b2, voffB); STAGE(SBo(0, 1), b2 + hstep, voffB); STAGE(SAo(0, 0), a2, voff);
;       WAIT_V(8); WAIT_L(0); BAR; MMA(1, 0, At, B0); MMA(1, 1, At, B1); BAR; SCHED;
;       LDB(B0, 1, 0); LDB(B1, 1, 1); SCHED; LDA(At, 1, 0); STAGE(SAo(0, 1), a2 + hstep, voff);
;       WAIT_V(8); WAIT_L(0); BAR; MMA(0, 0, At, B0); MMA(0, 1, At, B1); BAR; SCHED;
.Lkp_m1_1:
	s_mov_b32 s100, 0
	s_waitcnt lgkmcnt(0)
	s_barrier
	s_setprio 1
	s_waitcnt lgkmcnt(0)
	v_mfma_f32_16x16x32_bf16 v[62:65], v[130:133], v[182:185], v[62:65]
	v_mfma_f32_16x16x32_bf16 v[58:61], v[138:141], v[182:185], v[58:61]
	v_mfma_f32_16x16x32_bf16 v[46:49], v[130:133], v[190:193], v[46:49]
	v_mfma_f32_16x16x32_bf16 v[42:45], v[138:141], v[190:193], v[42:45]
	v_mfma_f32_16x16x32_bf16 v[30:33], v[130:133], v[198:201], v[30:33]
	v_mfma_f32_16x16x32_bf16 v[26:29], v[138:141], v[198:201], v[26:29]
	v_mfma_f32_16x16x32_bf16 v[14:17], v[130:133], v[206:209], v[14:17]
	v_mfma_f32_16x16x32_bf16 v[10:13], v[138:141], v[206:209], v[10:13]
	v_mfma_f32_16x16x32_bf16 v[62:65], v[134:137], v[186:189], v[62:65]
	v_mfma_f32_16x16x32_bf16 v[58:61], v[142:145], v[186:189], v[58:61]
	v_mfma_f32_16x16x32_bf16 v[46:49], v[134:137], v[194:197], v[46:49]
	v_mfma_f32_16x16x32_bf16 v[42:45], v[142:145], v[194:197], v[42:45]
	v_mfma_f32_16x16x32_bf16 v[30:33], v[134:137], v[202:205], v[30:33]
	v_mfma_f32_16x16x32_bf16 v[26:29], v[142:145], v[202:205], v[26:29]
	v_mfma_f32_16x16x32_bf16 v[14:17], v[134:137], v[210:213], v[14:17]
	v_mfma_f32_16x16x32_bf16 v[10:13], v[142:145], v[210:213], v[10:13]
	s_setprio 0
	s_setprio 1
	v_mfma_f32_16x16x32_bf16 v[54:57], v[160:163], v[182:185], v[54:57]
	v_mfma_f32_16x16x32_bf16 v[50:53], v[168:171], v[182:185], v[50:53]
	v_mfma_f32_16x16x32_bf16 v[38:41], v[160:163], v[190:193], v[38:41]
	v_mfma_f32_16x16x32_bf16 v[34:37], v[168:171], v[190:193], v[34:37]
	v_mfma_f32_16x16x32_bf16 v[22:25], v[160:163], v[198:201], v[22:25]
	v_mfma_f32_16x16x32_bf16 v[18:21], v[168:171], v[198:201], v[18:21]
	v_mfma_f32_16x16x32_bf16 v[6:9], v[160:163], v[206:209], v[6:9]
	v_mfma_f32_16x16x32_bf16 v[2:5], v[168:171], v[206:209], v[2:5]
	v_mfma_f32_16x16x32_bf16 v[54:57], v[164:167], v[186:189], v[54:57]
	v_mfma_f32_16x16x32_bf16 v[50:53], v[178:181], v[186:189], v[50:53]
	v_mfma_f32_16x16x32_bf16 v[38:41], v[164:167], v[194:197], v[38:41]
	v_mfma_f32_16x16x32_bf16 v[34:37], v[178:181], v[194:197], v[34:37]
	v_mfma_f32_16x16x32_bf16 v[22:25], v[164:167], v[202:205], v[22:25]
	v_mfma_f32_16x16x32_bf16 v[18:21], v[178:181], v[202:205], v[18:21]
	v_mfma_f32_16x16x32_bf16 v[6:9], v[164:167], v[210:213], v[6:9]
	v_mfma_f32_16x16x32_bf16 v[2:5], v[178:181], v[210:213], v[2:5]
	s_setprio 0
	s_barrier
	s_add_i32 s53, 0, 0x18000
	s_add_i32 s54, 0, 0x1c000
	v_add_u32_e32 v142, s53, v158
	v_add_u32_e32 v178, s54, v158
	ds_read_b128 v[130:133], v142
	ds_read_b128 v[134:137], v142 offset:1024
	ds_read_b128 v[138:141], v142 offset:2048
	ds_read_b128 v[142:145], v142 offset:3072
	ds_read_b128 v[160:163], v178
	ds_read_b128 v[164:167], v178 offset:1024
	ds_read_b128 v[168:171], v178 offset:2048
	ds_read_b128 v[178:181], v178 offset:3072
	s_add_u32 s24, s24, 0x40000
	s_addc_u32 s25, s25, 0
	s_mov_b32 m0, s31
	v_lshl_add_u64 v[220:221], s[24:25], 0, v[150:151]
	ds_read_b128 v[182:185], v159 offset:32768
	ds_read_b128 v[186:189], v159 offset:33792
	ds_read_b128 v[190:193], v159 offset:34816
	ds_read_b128 v[194:197], v159 offset:35840
	ds_read_b128 v[198:201], v159 offset:36864
	ds_read_b128 v[202:205], v159 offset:37888
	ds_read_b128 v[206:209], v159 offset:38912
	ds_read_b128 v[210:213], v159 offset:39936
	global_load_lds_dwordx4 v[220:221], off
	v_lshl_add_u64 v[220:221], s[24:25], 0, v[148:149]
	s_mov_b32 m0, s33
	s_nop 0
	global_load_lds_dwordx4 v[220:221], off
	s_waitcnt vmcnt(8)
	s_waitcnt lgkmcnt(0)
	s_barrier
	s_setprio 1
	s_waitcnt lgkmcnt(0)
	v_mfma_f32_16x16x32_bf16 v[126:129], v[130:133], v[182:185], v[126:129]
	v_mfma_f32_16x16x32_bf16 v[122:125], v[138:141], v[182:185], v[122:125]
	v_mfma_f32_16x16x32_bf16 v[110:113], v[130:133], v[190:193], v[110:113]
	v_mfma_f32_16x16x32_bf16 v[106:109], v[138:141], v[190:193], v[106:109]
	v_mfma_f32_16x16x32_bf16 v[94:97], v[130:133], v[198:201], v[94:97]
	v_mfma_f32_16x16x32_bf16 v[90:93], v[138:141], v[198:201], v[90:93]
	v_mfma_f32_16x16x32_bf16 v[78:81], v[130:133], v[206:209], v[78:81]
	v_mfma_f32_16x16x32_bf16 v[74:77], v[138:141], v[206:209], v[74:77]
	v_mfma_f32_16x16x32_bf16 v[126:129], v[134:137], v[186:189], v[126:129]
	v_mfma_f32_16x16x32_bf16 v[122:125], v[142:145], v[186:189], v[122:125]
	v_mfma_f32_16x16x32_bf16 v[110:113], v[134:137], v[194:197], v[110:113]
	v_mfma_f32_16x16x32_bf16 v[106:109], v[142:145], v[194:197], v[106:109]
	v_mfma_f32_16x16x32_bf16 v[94:97], v[134:137], v[202:205], v[94:97]
	v_mfma_f32_16x16x32_bf16 v[90:93], v[142:145], v[202:205], v[90:93]
	v_mfma_f32_16x16x32_bf16 v[78:81], v[134:137], v[210:213], v[78:81]
	v_mfma_f32_16x16x32_bf16 v[74:77], v[142:145], v[210:213], v[74:77]
	s_setprio 0
	s_setprio 1
	v_mfma_f32_16x16x32_bf16 v[118:121], v[160:163], v[182:185], v[118:121]
	v_mfma_f32_16x16x32_bf16 v[114:117], v[168:171], v[182:185], v[114:117]
	v_mfma_f32_16x16x32_bf16 v[102:105], v[160:163], v[190:193], v[102:105]
	v_mfma_f32_16x16x32_bf16 v[98:101], v[168:171], v[190:193], v[98:101]
	v_mfma_f32_16x16x32_bf16 v[86:89], v[160:163], v[198:201], v[86:89]
	v_mfma_f32_16x16x32_bf16 v[82:85], v[168:171], v[198:201], v[82:85]
	v_mfma_f32_16x16x32_bf16 v[70:73], v[160:163], v[206:209], v[70:73]
	v_mfma_f32_16x16x32_bf16 v[66:69], v[168:171], v[206:209], v[66:69]
	v_mfma_f32_16x16x32_bf16 v[118:121], v[164:167], v[186:189], v[118:121]
	v_mfma_f32_16x16x32_bf16 v[114:117], v[178:181], v[186:189], v[114:117]
	v_mfma_f32_16x16x32_bf16 v[102:105], v[164:167], v[194:197], v[102:105]
	v_mfma_f32_16x16x32_bf16 v[98:101], v[178:181], v[194:197], v[98:101]
	v_mfma_f32_16x16x32_bf16 v[86:89], v[164:167], v[202:205], v[86:89]
	v_mfma_f32_16x16x32_bf16 v[82:85], v[178:181], v[202:205], v[82:85]
	v_mfma_f32_16x16x32_bf16 v[70:73], v[164:167], v[210:213], v[70:73]
	v_mfma_f32_16x16x32_bf16 v[66:69], v[178:181], v[210:213], v[66:69]
	s_setprio 0
	s_barrier
; #define WAIT_V(n) asm volatile("s_waitcnt vmcnt(" #n ")" ::: "memory")
; #define WAIT_L(n) asm volatile("s_waitcnt lgkmcnt(" #n ")" ::: "memory")
; #define BAR __builtin_amdgcn_s_barrier()
; #define SCHED __builtin_amdgcn_sched_barrier(0)
; template <int EPI>
; DI void gemm_epilogue(const Params& p, int layer, f32x4 (&acc)[2][2][4][2], int brow, int bcol, int pn, int wr, int wc,
;                       int fr, int fq, char* smem, int ksplit = -1) {
;     ...
;     const int bidx = (brow < NLAT) ? (brow >> 11) : 16;
;     const float* bias = p.bias1 + (size_t)(layer * 17 + bidx) * HID;
;     const int colb = bcol + wc * 32 + fq * 8;
;     f32x4 bv[2][2];
;     float rsv[2][4];
; #pragma unroll
;     for (int bj = 0; bj < 2; ++bj)
; #pragma unroll
;       for (int n = 0; n < 2; ++n) bv[bj][n] = *(const f32x4*)(bias + colb + bj * 128 + n * 4);
; #pragma unroll
;     for (int ai = 0; ai < 2; ++ai)
; #pragma unroll
;       for (int m = 0; m < 4; ++m) rsv[ai][m] = p.rowss[(size_t)layer * NTOK + brow + ai * 128 + wr * 64 + m * 16 + fr];
;     ...
;       LDA(At, 1, 1); STAGE(SBo(1, 0), b3, voffB); STAGE(SBo(1, 1), b3 + hstep, voffB); STAGE(SAo(1, 0), a3, voff);
;       WAIT_V(8); WAIT_L(0); BAR; MMA(1, 0, At, B0); MMA(1, 1, At, B1); BAR; SCHED;
;     }
;     if (wr == 0) BAR;
	s_add_i32 s24, s53, s29
	v_lshl_add_u64 v[156:157], v[156:157], 0, s[34:35]
	s_mov_b32 m0, s24
	ds_read_b128 v[182:185], v159 offset:49152
	ds_read_b128 v[186:189], v159 offset:50176
	ds_read_b128 v[190:193], v159 offset:51200
	ds_read_b128 v[194:197], v159 offset:52224
	ds_read_b128 v[198:201], v159 offset:53248
	ds_read_b128 v[202:205], v159 offset:54272
	ds_read_b128 v[206:209], v159 offset:55296
	ds_read_b128 v[210:213], v159 offset:56320
	global_load_lds_dwordx4 v[156:157], off
	s_add_i32 m0, s24, 0x2000
	s_add_u32 s22, s22, 0x40080
	v_lshl_add_u64 v[156:157], v[214:215], 0, s[34:35]
	s_addc_u32 s23, s23, 0
	s_add_i32 s24, s54, s29
	global_load_lds_dwordx4 v[156:157], off
	v_lshl_add_u64 v[156:157], s[22:23], 0, v[0:1]
	s_mov_b32 m0, s24
	s_nop 0
	global_load_lds_dwordx4 v[156:157], off
	v_lshl_add_u64 v[156:157], s[22:23], 0, v[146:147]
	s_add_i32 m0, s24, 0x2000
	s_nop 0
	global_load_lds_dwordx4 v[156:157], off
	v_lshl_add_u64 v[156:157], v[216:217], 0, s[34:35]
	s_mov_b32 m0, s42
	s_nop 0
	global_load_lds_dwordx4 v[156:157], off
	v_lshl_add_u64 v[156:157], v[218:219], 0, s[34:35]
	s_mov_b32 m0, s43
	s_nop 0
	global_load_lds_dwordx4 v[156:157], off
	s_waitcnt vmcnt(8)
	s_waitcnt lgkmcnt(0)
	s_barrier
	s_setprio 1
	s_waitcnt lgkmcnt(0)
	v_mfma_f32_16x16x32_bf16 v[62:65], v[130:133], v[182:185], v[62:65]
	v_mfma_f32_16x16x32_bf16 v[58:61], v[138:141], v[182:185], v[58:61]
	v_mfma_f32_16x16x32_bf16 v[46:49], v[130:133], v[190:193], v[46:49]
	v_mfma_f32_16x16x32_bf16 v[42:45], v[138:141], v[190:193], v[42:45]
	v_mfma_f32_16x16x32_bf16 v[30:33], v[130:133], v[198:201], v[30:33]
	v_mfma_f32_16x16x32_bf16 v[26:29], v[138:141], v[198:201], v[26:29]
	v_mfma_f32_16x16x32_bf16 v[14:17], v[130:133], v[206:209], v[14:17]
	v_mfma_f32_16x16x32_bf16 v[10:13], v[138:141], v[206:209], v[10:13]
	v_mfma_f32_16x16x32_bf16 v[62:65], v[134:137], v[186:189], v[62:65]
	v_mfma_f32_16x16x32_bf16 v[58:61], v[142:145], v[186:189], v[58:61]
	v_mfma_f32_16x16x32_bf16 v[46:49], v[134:137], v[194:197], v[46:49]
	v_mfma_f32_16x16x32_bf16 v[42:45], v[142:145], v[194:197], v[42:45]
	v_mfma_f32_16x16x32_bf16 v[30:33], v[134:137], v[202:205], v[30:33]
	v_mfma_f32_16x16x32_bf16 v[26:29], v[142:145], v[202:205], v[26:29]
	v_mfma_f32_16x16x32_bf16 v[14:17], v[134:137], v[210:213], v[14:17]
	v_mfma_f32_16x16x32_bf16 v[10:13], v[142:145], v[210:213], v[10:13]
	s_setprio 0
	s_setprio 1
	v_mfma_f32_16x16x32_bf16 v[54:57], v[160:163], v[182:185], v[54:57]
	v_mfma_f32_16x16x32_bf16 v[50:53], v[168:171], v[182:185], v[50:53]
	v_mfma_f32_16x16x32_bf16 v[38:41], v[160:163], v[190:193], v[38:41]
	v_mfma_f32_16x16x32_bf16 v[34:37], v[168:171], v[190:193], v[34:37]
	v_mfma_f32_16x16x32_bf16 v[22:25], v[160:163], v[198:201], v[22:25]
	v_mfma_f32_16x16x32_bf16 v[18:21], v[168:171], v[198:201], v[18:21]
	v_mfma_f32_16x16x32_bf16 v[6:9], v[160:163], v[206:209], v[6:9]
	v_mfma_f32_16x16x32_bf16 v[2:5], v[168:171], v[206:209], v[2:5]
	v_mfma_f32_16x16x32_bf16 v[54:57], v[164:167], v[186:189], v[54:57]
	v_mfma_f32_16x16x32_bf16 v[50:53], v[178:181], v[186:189], v[50:53]
	v_mfma_f32_16x16x32_bf16 v[38:41], v[164:167], v[194:197], v[38:41]
	v_mfma_f32_16x16x32_bf16 v[34:37], v[178:181], v[194:197], v[34:37]
	v_mfma_f32_16x16x32_bf16 v[22:25], v[164:167], v[202:205], v[22:25]
	v_mfma_f32_16x16x32_bf16 v[18:21], v[178:181], v[202:205], v[18:21]
	v_mfma_f32_16x16x32_bf16 v[6:9], v[164:167], v[210:213], v[6:9]
	v_mfma_f32_16x16x32_bf16 v[2:5], v[178:181], v[210:213], v[2:5]
	s_setprio 0
	s_barrier
	s_add_i32 s52, s52, 2
	s_add_u32 s20, s20, 0x100
	s_addc_u32 s21, s21, 0
	s_add_u32 s50, s50, 0x100
	s_addc_u32 s51, s51, 0
	s_cmp_gt_u32 s52, 13
	s_cbranch_scc0 .LBB0_994
	s_and_b64 vcc, exec, s[8:9]
	s_cbranch_vccz .LBB0_997
	s_barrier
.LBB0_997:
	s_lshl_b32 s20, s18, 8
	s_min_i32 s13, s20, 0x8000
	v_mov_b32_e32 v130, v234
	s_ashr_i32 s13, s13, 11
	v_readlane_b32 s18, v255, 10
	s_add_i32 s22, s13, s18
	s_lshl_b32 s11, s47, 8
	v_and_b32_e32 v156, 15, v130
	s_ashr_i32 s23, s22, 31
	v_lshrrev_b32_e32 v130, 1, v130
	s_lshl_b64 s[22:23], s[22:23], 14
	v_and_or_b32 v130, v130, 24, s11
	s_add_u32 s22, s90, s22
	v_or_b32_e32 v162, s39, v130
	s_addc_u32 s23, s91, s23
	v_ashrrev_i32_e32 v163, 31, v162
	s_ashr_i32 s21, s20, 31
	v_lshl_add_u64 v[134:135], v[162:163], 2, s[22:23]
	s_lshl_b64 s[22:23], s[20:21], 2
	s_add_u32 s22, s7, s22
	s_addc_u32 s23, s44, s23
	v_lshlrev_b32_e32 v157, 2, v156
	global_load_dwordx4 v[138:141], v[134:135], off offset:16
	global_load_dwordx4 v[142:145], v[134:135], off
	global_load_dwordx4 v[130:133], v[134:135], off offset:528
	s_nop 0
	global_load_dwordx4 v[134:137], v[134:135], off offset:512
	s_nop 0
	global_load_dword v164, v157, s[22:23]
	global_load_dword v165, v157, s[22:23] offset:64
	global_load_dword v168, v157, s[22:23] offset:128
	global_load_dword v169, v157, s[22:23] offset:192
	global_load_dword v170, v157, s[22:23] offset:512
	global_load_dword v171, v157, s[22:23] offset:576
	global_load_dword v161, v157, s[22:23] offset:640
	global_load_dword v160, v157, s[22:23] offset:704
	s_add_i32 s11, s20, s6
	v_bfe_u32 v181, v234, 2, 4
	v_or_b32_e32 v156, s11, v181
	v_and_b32_e32 v180, 3, v234
	v_and_b32_e32 v182, 0xffffffe7, v162
	v_lshl_or_b32 v182, v180, 3, v182
	v_mov_b32_e32 v183, 0
	v_lshl_or_b32 v180, v180, 4, v181
	v_lshlrev_b32_e32 v180, 2, v180
	s_waitcnt vmcnt(0)
; template <int EPI>
; DI void gemm_epilogue(const Params& p, int layer, f32x4 (&acc)[2][2][4][2], int brow, int bcol, int pn, int wr, int wc,
;                       int fr, int fq, char* smem, int ksplit = -1) {
;     ...
; #pragma unroll
;     for (int ai = 0; ai < 2; ++ai)
; #pragma unroll
;       for (int m = 0; m < 4; ++m) {
;         __builtin_amdgcn_sched_barrier(0);
;         const int row = brow + ai * 128 + wr * 64 + m * 16 + fr;
;         const float rs = __builtin_amdgcn_rsqf(rsv[ai][m] * (1.f / DM) + EPSN);
; #pragma unroll
;         for (int bj = 0; bj < 2; ++bj) {
;           u32x4 o;
; #pragma unroll
;           for (int n = 0; n < 2; ++n) {
;             f32x4 v = acc[ai][bj][m][n] * rs + bv[bj][n];
; #pragma unroll
;             for (int j = 0; j < 4; ++j) {
;               float r = fmaxf(v[j], 0.f);
;               v[j] = r * r;
;             }
;             o[2 * n] = pk_bf16(v[0], v[1]);
;             o[2 * n + 1] = pk_bf16(v[2], v[3]);
;           }
;           *(u32x4*)(p.hid + (size_t)row * HID + colb + bj * 128) = o;
;         }
	s_mov_b32 s100, 1
	v_fmamk_f32 v157, v164, 0x3a800000, v236
	v_rsq_f32_e32 v164, v157
	v_ashrrev_i32_e32 v157, 31, v156
	v_lshlrev_b64 v[166:167], 13, v[156:157]
	v_pk_fma_f32 v[128:129], v[128:129], v[164:165], v[144:145] op_sel_hi:[1,0,1]
	v_pk_fma_f32 v[126:127], v[126:127], v[164:165], v[142:143] op_sel_hi:[1,0,1]
	v_pk_fma_f32 v[124:125], v[124:125], v[164:165], v[140:141] op_sel_hi:[1,0,1]
	v_pk_fma_f32 v[122:123], v[122:123], v[164:165], v[138:139] op_sel_hi:[1,0,1]
	v_max_f32_e32 v126, 0, v126
	v_max_f32_e32 v127, 0, v127
	v_max_f32_e32 v128, 0, v128
	v_max_f32_e32 v129, 0, v129
	v_max_f32_e32 v122, 0, v122
	v_max_f32_e32 v123, 0, v123
	v_max_f32_e32 v124, 0, v124
	v_max_f32_e32 v125, 0, v125
	v_pk_fma_f32 v[120:121], v[120:121], v[164:165], v[136:137] op_sel_hi:[1,0,1]
	v_pk_fma_f32 v[118:119], v[118:119], v[164:165], v[134:135] op_sel_hi:[1,0,1]
	v_pk_fma_f32 v[116:117], v[116:117], v[164:165], v[132:133] op_sel_hi:[1,0,1]
	v_pk_fma_f32 v[114:115], v[114:115], v[164:165], v[130:131] op_sel_hi:[1,0,1]
	v_pk_mul_f32 v[126:127], v[126:127], v[126:127]
	v_pk_mul_f32 v[128:129], v[128:129], v[128:129]
	v_pk_mul_f32 v[122:123], v[122:123], v[122:123]
	v_pk_mul_f32 v[124:125], v[124:125], v[124:125]
	v_max_f32_e32 v118, 0, v118
	v_max_f32_e32 v119, 0, v119
	v_max_f32_e32 v120, 0, v120
	v_max_f32_e32 v121, 0, v121
	v_max_f32_e32 v114, 0, v114
	v_max_f32_e32 v115, 0, v115
	v_max_f32_e32 v116, 0, v116
	v_max_f32_e32 v117, 0, v117
	v_cvt_pk_bf16_f32 v126, v126, v127
	v_cvt_pk_bf16_f32 v127, v128, v129
	v_cvt_pk_bf16_f32 v128, v122, v123
	v_cvt_pk_bf16_f32 v129, v124, v125
	v_lshl_add_u64 v[124:125], s[84:85], 0, v[166:167]
	v_lshlrev_b64 v[122:123], 1, v[182:183]
	v_pk_mul_f32 v[118:119], v[118:119], v[118:119]
	v_pk_mul_f32 v[120:121], v[120:121], v[120:121]
	v_pk_mul_f32 v[114:115], v[114:115], v[114:115]
	v_pk_mul_f32 v[116:117], v[116:117], v[116:117]
	v_lshl_add_u64 v[124:125], v[124:125], 0, v[122:123]
	v_cvt_pk_bf16_f32 v118, v118, v119
	v_cvt_pk_bf16_f32 v119, v120, v121
	v_cvt_pk_bf16_f32 v120, v114, v115
	v_cvt_pk_bf16_f32 v121, v116, v117
	ds_bpermute_b32 v126, v180, v126
	ds_bpermute_b32 v127, v180, v127
	ds_bpermute_b32 v128, v180, v128
	ds_bpermute_b32 v129, v180, v129
	ds_bpermute_b32 v118, v180, v118
	ds_bpermute_b32 v119, v180, v119
	ds_bpermute_b32 v120, v180, v120
	ds_bpermute_b32 v121, v180, v121
	v_fmamk_f32 v114, v165, 0x3a800000, v236
	v_rsq_f32_e32 v114, v114
	v_or_b32_e32 v116, 16, v156
	v_ashrrev_i32_e32 v117, 31, v116
	v_lshlrev_b64 v[116:117], 13, v[116:117]
	v_pk_fma_f32 v[112:113], v[112:113], v[114:115], v[144:145] op_sel_hi:[1,0,1]
	v_pk_fma_f32 v[110:111], v[110:111], v[114:115], v[142:143] op_sel_hi:[1,0,1]
	v_pk_fma_f32 v[106:107], v[106:107], v[114:115], v[138:139] op_sel_hi:[1,0,1]
	v_max_f32_e32 v110, 0, v110
	v_max_f32_e32 v111, 0, v111
	v_max_f32_e32 v112, 0, v112
	v_max_f32_e32 v113, 0, v113
	v_pk_fma_f32 v[108:109], v[108:109], v[114:115], v[140:141] op_sel_hi:[1,0,1]
	v_max_f32_e32 v106, 0, v106
	v_max_f32_e32 v107, 0, v107
	v_pk_fma_f32 v[104:105], v[104:105], v[114:115], v[136:137] op_sel_hi:[1,0,1]
	v_pk_fma_f32 v[102:103], v[102:103], v[114:115], v[134:135] op_sel_hi:[1,0,1]
	v_pk_fma_f32 v[100:101], v[100:101], v[114:115], v[132:133] op_sel_hi:[1,0,1]
	v_pk_fma_f32 v[98:99], v[98:99], v[114:115], v[130:131] op_sel_hi:[1,0,1]
	v_pk_mul_f32 v[110:111], v[110:111], v[110:111]
	v_pk_mul_f32 v[112:113], v[112:113], v[112:113]
	v_pk_mul_f32 v[106:107], v[106:107], v[106:107]
	v_max_f32_e32 v108, 0, v108
	v_max_f32_e32 v109, 0, v109
	v_max_f32_e32 v102, 0, v102
	v_max_f32_e32 v103, 0, v103
	v_max_f32_e32 v104, 0, v104
	v_max_f32_e32 v105, 0, v105
	v_max_f32_e32 v98, 0, v98
	v_max_f32_e32 v99, 0, v99
	v_max_f32_e32 v100, 0, v100
	v_max_f32_e32 v101, 0, v101
	v_cvt_pk_bf16_f32 v110, v110, v111
	v_cvt_pk_bf16_f32 v111, v112, v113
	v_pk_mul_f32 v[108:109], v[108:109], v[108:109]
	v_cvt_pk_bf16_f32 v112, v106, v107
	v_lshl_add_u64 v[106:107], s[84:85], 0, v[116:117]
	v_pk_mul_f32 v[102:103], v[102:103], v[102:103]
	v_pk_mul_f32 v[104:105], v[104:105], v[104:105]
	v_pk_mul_f32 v[98:99], v[98:99], v[98:99]
	v_pk_mul_f32 v[100:101], v[100:101], v[100:101]
	v_cvt_pk_bf16_f32 v113, v108, v109
	v_lshl_add_u64 v[106:107], v[106:107], 0, v[122:123]
	v_cvt_pk_bf16_f32 v102, v102, v103
	v_cvt_pk_bf16_f32 v103, v104, v105
	v_cvt_pk_bf16_f32 v104, v98, v99
	v_cvt_pk_bf16_f32 v105, v100, v101
	s_waitcnt lgkmcnt(0)
	global_store_dwordx4 v[124:125], v[126:129], off
	global_store_dwordx4 v[124:125], v[118:121], off offset:256
	ds_bpermute_b32 v110, v180, v110
	ds_bpermute_b32 v111, v180, v111
	ds_bpermute_b32 v112, v180, v112
	ds_bpermute_b32 v113, v180, v113
	ds_bpermute_b32 v102, v180, v102
	ds_bpermute_b32 v103, v180, v103
	ds_bpermute_b32 v104, v180, v104
	ds_bpermute_b32 v105, v180, v105
	v_fmamk_f32 v98, v168, 0x3a800000, v236
	v_rsq_f32_e32 v98, v98
	v_or_b32_e32 v100, 32, v156
	v_ashrrev_i32_e32 v101, 31, v100
	v_lshlrev_b64 v[100:101], 13, v[100:101]
	v_pk_fma_f32 v[96:97], v[96:97], v[98:99], v[144:145] op_sel_hi:[1,0,1]
	v_pk_fma_f32 v[94:95], v[94:95], v[98:99], v[142:143] op_sel_hi:[1,0,1]
	v_pk_fma_f32 v[90:91], v[90:91], v[98:99], v[138:139] op_sel_hi:[1,0,1]
	v_max_f32_e32 v94, 0, v94
	v_max_f32_e32 v95, 0, v95
	v_max_f32_e32 v96, 0, v96
	v_max_f32_e32 v97, 0, v97
	v_pk_fma_f32 v[92:93], v[92:93], v[98:99], v[140:141] op_sel_hi:[1,0,1]
	v_max_f32_e32 v90, 0, v90
	v_max_f32_e32 v91, 0, v91
	v_pk_fma_f32 v[88:89], v[88:89], v[98:99], v[136:137] op_sel_hi:[1,0,1]
	v_pk_fma_f32 v[86:87], v[86:87], v[98:99], v[134:135] op_sel_hi:[1,0,1]
	v_pk_fma_f32 v[84:85], v[84:85], v[98:99], v[132:133] op_sel_hi:[1,0,1]
	v_pk_fma_f32 v[82:83], v[82:83], v[98:99], v[130:131] op_sel_hi:[1,0,1]
	v_pk_mul_f32 v[94:95], v[94:95], v[94:95]
	v_pk_mul_f32 v[96:97], v[96:97], v[96:97]
	v_pk_mul_f32 v[90:91], v[90:91], v[90:91]
	v_max_f32_e32 v92, 0, v92
	v_max_f32_e32 v93, 0, v93
	v_max_f32_e32 v86, 0, v86
	v_max_f32_e32 v87, 0, v87
	v_max_f32_e32 v88, 0, v88
	v_max_f32_e32 v89, 0, v89
	v_max_f32_e32 v82, 0, v82
	v_max_f32_e32 v83, 0, v83
	v_max_f32_e32 v84, 0, v84
	v_max_f32_e32 v85, 0, v85
	v_cvt_pk_bf16_f32 v94, v94, v95
	v_cvt_pk_bf16_f32 v95, v96, v97
	v_pk_mul_f32 v[92:93], v[92:93], v[92:93]
	v_cvt_pk_bf16_f32 v96, v90, v91
	v_lshl_add_u64 v[90:91], s[84:85], 0, v[100:101]
	v_pk_mul_f32 v[86:87], v[86:87], v[86:87]
	v_pk_mul_f32 v[88:89], v[88:89], v[88:89]
	v_pk_mul_f32 v[82:83], v[82:83], v[82:83]
	v_pk_mul_f32 v[84:85], v[84:85], v[84:85]
	v_cvt_pk_bf16_f32 v97, v92, v93
	v_lshl_add_u64 v[90:91], v[90:91], 0, v[122:123]
	v_cvt_pk_bf16_f32 v86, v86, v87
	v_cvt_pk_bf16_f32 v87, v88, v89
	v_cvt_pk_bf16_f32 v88, v82, v83
	v_cvt_pk_bf16_f32 v89, v84, v85
	s_waitcnt lgkmcnt(0)
; template <int EPI>
; DI void gemm_epilogue(const Params& p, int layer, f32x4 (&acc)[2][2][4][2], int brow, int bcol, int pn, int wr, int wc,
;                       int fr, int fq, char* smem, int ksplit = -1) {
;     ...
; #pragma unroll
;     for (int ai = 0; ai < 2; ++ai)
; #pragma unroll
;       for (int m = 0; m < 4; ++m) {
;         __builtin_amdgcn_sched_barrier(0);
;         const int row = brow + ai * 128 + wr * 64 + m * 16 + fr;
;         const float rs = __builtin_amdgcn_rsqf(rsv[ai][m] * (1.f / DM) + EPSN);
; #pragma unroll
;         for (int bj = 0; bj < 2; ++bj) {
;           u32x4 o;
; #pragma unroll
;           for (int n = 0; n < 2; ++n) {
;             f32x4 v = acc[ai][bj][m][n] * rs + bv[bj][n];
; #pragma unroll
;             for (int j = 0; j < 4; ++j) {
;               float r = fmaxf(v[j], 0.f);
;               v[j] = r * r;
;             }
;             o[2 * n] = pk_bf16(v[0], v[1]);
;             o[2 * n + 1] = pk_bf16(v[2], v[3]);
;           }
;           *(u32x4*)(p.hid + (size_t)row * HID + colb + bj * 128) = o;
;         }
	global_store_dwordx4 v[106:107], v[110:113], off
	global_store_dwordx4 v[106:107], v[102:105], off offset:256
	ds_bpermute_b32 v94, v180, v94
	ds_bpermute_b32 v95, v180, v95
	ds_bpermute_b32 v96, v180, v96
	ds_bpermute_b32 v97, v180, v97
	ds_bpermute_b32 v86, v180, v86
	ds_bpermute_b32 v87, v180, v87
	ds_bpermute_b32 v88, v180, v88
	ds_bpermute_b32 v89, v180, v89
	v_fmamk_f32 v82, v169, 0x3a800000, v236
	v_rsq_f32_e32 v82, v82
	v_or_b32_e32 v84, 48, v156
	v_ashrrev_i32_e32 v85, 31, v84
	v_lshlrev_b64 v[84:85], 13, v[84:85]
	v_pk_fma_f32 v[80:81], v[80:81], v[82:83], v[144:145] op_sel_hi:[1,0,1]
	v_pk_fma_f32 v[78:79], v[78:79], v[82:83], v[142:143] op_sel_hi:[1,0,1]
	v_pk_fma_f32 v[74:75], v[74:75], v[82:83], v[138:139] op_sel_hi:[1,0,1]
	v_max_f32_e32 v78, 0, v78
	v_max_f32_e32 v79, 0, v79
	v_max_f32_e32 v80, 0, v80
	v_max_f32_e32 v81, 0, v81
	v_pk_fma_f32 v[76:77], v[76:77], v[82:83], v[140:141] op_sel_hi:[1,0,1]
	v_max_f32_e32 v74, 0, v74
	v_max_f32_e32 v75, 0, v75
	v_pk_fma_f32 v[72:73], v[72:73], v[82:83], v[136:137] op_sel_hi:[1,0,1]
	v_pk_fma_f32 v[70:71], v[70:71], v[82:83], v[134:135] op_sel_hi:[1,0,1]
	v_pk_fma_f32 v[68:69], v[68:69], v[82:83], v[132:133] op_sel_hi:[1,0,1]
	v_pk_fma_f32 v[66:67], v[66:67], v[82:83], v[130:131] op_sel_hi:[1,0,1]
	v_pk_mul_f32 v[78:79], v[78:79], v[78:79]
	v_pk_mul_f32 v[80:81], v[80:81], v[80:81]
	v_pk_mul_f32 v[74:75], v[74:75], v[74:75]
	v_max_f32_e32 v76, 0, v76
	v_max_f32_e32 v77, 0, v77
	v_max_f32_e32 v70, 0, v70
	v_max_f32_e32 v71, 0, v71
	v_max_f32_e32 v72, 0, v72
	v_max_f32_e32 v73, 0, v73
	v_max_f32_e32 v66, 0, v66
	v_max_f32_e32 v67, 0, v67
	v_max_f32_e32 v68, 0, v68
	v_max_f32_e32 v69, 0, v69
	v_cvt_pk_bf16_f32 v78, v78, v79
	v_cvt_pk_bf16_f32 v79, v80, v81
	v_pk_mul_f32 v[76:77], v[76:77], v[76:77]
	v_cvt_pk_bf16_f32 v80, v74, v75
	v_lshl_add_u64 v[74:75], s[84:85], 0, v[84:85]
	v_pk_mul_f32 v[70:71], v[70:71], v[70:71]
	v_pk_mul_f32 v[72:73], v[72:73], v[72:73]
	v_pk_mul_f32 v[66:67], v[66:67], v[66:67]
	v_pk_mul_f32 v[68:69], v[68:69], v[68:69]
	v_cvt_pk_bf16_f32 v81, v76, v77
	v_lshl_add_u64 v[74:75], v[74:75], 0, v[122:123]
	v_cvt_pk_bf16_f32 v70, v70, v71
	v_cvt_pk_bf16_f32 v71, v72, v73
	v_cvt_pk_bf16_f32 v72, v66, v67
	v_cvt_pk_bf16_f32 v73, v68, v69
	s_waitcnt lgkmcnt(0)
	global_store_dwordx4 v[90:91], v[94:97], off
	global_store_dwordx4 v[90:91], v[86:89], off offset:256
	ds_bpermute_b32 v78, v180, v78
	ds_bpermute_b32 v79, v180, v79
	ds_bpermute_b32 v80, v180, v80
	ds_bpermute_b32 v81, v180, v81
	ds_bpermute_b32 v70, v180, v70
	ds_bpermute_b32 v71, v180, v71
	ds_bpermute_b32 v72, v180, v72
	ds_bpermute_b32 v73, v180, v73
	v_add_u32_e32 v66, 0x80, v156
	v_fmamk_f32 v67, v170, 0x3a800000, v236
	v_rsq_f32_e32 v68, v67
	v_ashrrev_i32_e32 v67, 31, v66
	v_lshlrev_b64 v[66:67], 13, v[66:67]
	v_pk_fma_f32 v[64:65], v[64:65], v[68:69], v[144:145] op_sel_hi:[1,0,1]
	v_pk_fma_f32 v[62:63], v[62:63], v[68:69], v[142:143] op_sel_hi:[1,0,1]
	v_pk_fma_f32 v[58:59], v[58:59], v[68:69], v[138:139] op_sel_hi:[1,0,1]
	v_max_f32_e32 v62, 0, v62
	v_max_f32_e32 v63, 0, v63
	v_max_f32_e32 v64, 0, v64
	v_max_f32_e32 v65, 0, v65
	v_pk_fma_f32 v[60:61], v[60:61], v[68:69], v[140:141] op_sel_hi:[1,0,1]
	v_max_f32_e32 v58, 0, v58
	v_max_f32_e32 v59, 0, v59
	v_pk_fma_f32 v[56:57], v[56:57], v[68:69], v[136:137] op_sel_hi:[1,0,1]
	v_pk_fma_f32 v[54:55], v[54:55], v[68:69], v[134:135] op_sel_hi:[1,0,1]
	v_pk_fma_f32 v[52:53], v[52:53], v[68:69], v[132:133] op_sel_hi:[1,0,1]
	v_pk_fma_f32 v[50:51], v[50:51], v[68:69], v[130:131] op_sel_hi:[1,0,1]
	v_pk_mul_f32 v[62:63], v[62:63], v[62:63]
	v_pk_mul_f32 v[64:65], v[64:65], v[64:65]
	v_pk_mul_f32 v[58:59], v[58:59], v[58:59]
	v_max_f32_e32 v60, 0, v60
	v_max_f32_e32 v61, 0, v61
	v_max_f32_e32 v54, 0, v54
	v_max_f32_e32 v55, 0, v55
	v_max_f32_e32 v56, 0, v56
	v_max_f32_e32 v57, 0, v57
	v_max_f32_e32 v50, 0, v50
	v_max_f32_e32 v51, 0, v51
	v_max_f32_e32 v52, 0, v52
	v_max_f32_e32 v53, 0, v53
	v_cvt_pk_bf16_f32 v62, v62, v63
	v_cvt_pk_bf16_f32 v63, v64, v65
	v_pk_mul_f32 v[60:61], v[60:61], v[60:61]
	v_cvt_pk_bf16_f32 v64, v58, v59
	v_lshl_add_u64 v[58:59], s[84:85], 0, v[66:67]
	v_pk_mul_f32 v[54:55], v[54:55], v[54:55]
	v_pk_mul_f32 v[56:57], v[56:57], v[56:57]
	v_pk_mul_f32 v[50:51], v[50:51], v[50:51]
	v_pk_mul_f32 v[52:53], v[52:53], v[52:53]
	v_cvt_pk_bf16_f32 v65, v60, v61
	v_lshl_add_u64 v[58:59], v[58:59], 0, v[122:123]
	v_cvt_pk_bf16_f32 v54, v54, v55
	v_cvt_pk_bf16_f32 v55, v56, v57
	v_cvt_pk_bf16_f32 v56, v50, v51
	v_cvt_pk_bf16_f32 v57, v52, v53
	s_waitcnt lgkmcnt(0)
; template <int EPI>
; DI void gemm_epilogue(const Params& p, int layer, f32x4 (&acc)[2][2][4][2], int brow, int bcol, int pn, int wr, int wc,
;                       int fr, int fq, char* smem, int ksplit = -1) {
;     ...
; #pragma unroll
;     for (int ai = 0; ai < 2; ++ai)
; #pragma unroll
;       for (int m = 0; m < 4; ++m) {
;         __builtin_amdgcn_sched_barrier(0);
;         const int row = brow + ai * 128 + wr * 64 + m * 16 + fr;
;         const float rs = __builtin_amdgcn_rsqf(rsv[ai][m] * (1.f / DM) + EPSN);
; #pragma unroll
;         for (int bj = 0; bj < 2; ++bj) {
;           u32x4 o;
; #pragma unroll
;           for (int n = 0; n < 2; ++n) {
;             f32x4 v = acc[ai][bj][m][n] * rs + bv[bj][n];
; #pragma unroll
;             for (int j = 0; j < 4; ++j) {
;               float r = fmaxf(v[j], 0.f);
;               v[j] = r * r;
;             }
;             o[2 * n] = pk_bf16(v[0], v[1]);
;             o[2 * n + 1] = pk_bf16(v[2], v[3]);
;           }
;           *(u32x4*)(p.hid + (size_t)row * HID + colb + bj * 128) = o;
;         }
	global_store_dwordx4 v[74:75], v[78:81], off
	global_store_dwordx4 v[74:75], v[70:73], off offset:256
	ds_bpermute_b32 v62, v180, v62
	ds_bpermute_b32 v63, v180, v63
	ds_bpermute_b32 v64, v180, v64
	ds_bpermute_b32 v65, v180, v65
	ds_bpermute_b32 v54, v180, v54
	ds_bpermute_b32 v55, v180, v55
	ds_bpermute_b32 v56, v180, v56
	ds_bpermute_b32 v57, v180, v57
	v_fmamk_f32 v50, v171, 0x3a800000, v236
	v_rsq_f32_e32 v50, v50
	v_add_u32_e32 v52, 0x90, v156
	v_ashrrev_i32_e32 v53, 31, v52
	v_lshlrev_b64 v[52:53], 13, v[52:53]
	v_pk_fma_f32 v[48:49], v[48:49], v[50:51], v[144:145] op_sel_hi:[1,0,1]
	v_pk_fma_f32 v[46:47], v[46:47], v[50:51], v[142:143] op_sel_hi:[1,0,1]
	v_pk_fma_f32 v[42:43], v[42:43], v[50:51], v[138:139] op_sel_hi:[1,0,1]
	v_max_f32_e32 v46, 0, v46
	v_max_f32_e32 v47, 0, v47
	v_max_f32_e32 v48, 0, v48
	v_max_f32_e32 v49, 0, v49
	v_pk_fma_f32 v[44:45], v[44:45], v[50:51], v[140:141] op_sel_hi:[1,0,1]
	v_max_f32_e32 v42, 0, v42
	v_max_f32_e32 v43, 0, v43
	v_pk_fma_f32 v[40:41], v[40:41], v[50:51], v[136:137] op_sel_hi:[1,0,1]
	v_pk_fma_f32 v[38:39], v[38:39], v[50:51], v[134:135] op_sel_hi:[1,0,1]
	v_pk_fma_f32 v[36:37], v[36:37], v[50:51], v[132:133] op_sel_hi:[1,0,1]
	v_pk_fma_f32 v[34:35], v[34:35], v[50:51], v[130:131] op_sel_hi:[1,0,1]
	v_pk_mul_f32 v[46:47], v[46:47], v[46:47]
	v_pk_mul_f32 v[48:49], v[48:49], v[48:49]
	v_pk_mul_f32 v[42:43], v[42:43], v[42:43]
	v_max_f32_e32 v44, 0, v44
	v_max_f32_e32 v45, 0, v45
	v_max_f32_e32 v38, 0, v38
	v_max_f32_e32 v39, 0, v39
	v_max_f32_e32 v40, 0, v40
	v_max_f32_e32 v41, 0, v41
	v_max_f32_e32 v34, 0, v34
	v_max_f32_e32 v35, 0, v35
	v_max_f32_e32 v36, 0, v36
	v_max_f32_e32 v37, 0, v37
	v_cvt_pk_bf16_f32 v46, v46, v47
	v_cvt_pk_bf16_f32 v47, v48, v49
	v_pk_mul_f32 v[44:45], v[44:45], v[44:45]
	v_cvt_pk_bf16_f32 v48, v42, v43
	v_lshl_add_u64 v[42:43], s[84:85], 0, v[52:53]
	v_pk_mul_f32 v[38:39], v[38:39], v[38:39]
	v_pk_mul_f32 v[40:41], v[40:41], v[40:41]
	v_pk_mul_f32 v[34:35], v[34:35], v[34:35]
	v_pk_mul_f32 v[36:37], v[36:37], v[36:37]
	v_cvt_pk_bf16_f32 v49, v44, v45
	v_lshl_add_u64 v[42:43], v[42:43], 0, v[122:123]
	v_cvt_pk_bf16_f32 v38, v38, v39
	v_cvt_pk_bf16_f32 v39, v40, v41
	v_cvt_pk_bf16_f32 v40, v34, v35
	v_cvt_pk_bf16_f32 v41, v36, v37
	s_waitcnt lgkmcnt(0)
	global_store_dwordx4 v[58:59], v[62:65], off
	global_store_dwordx4 v[58:59], v[54:57], off offset:256
	ds_bpermute_b32 v46, v180, v46
	ds_bpermute_b32 v47, v180, v47
	ds_bpermute_b32 v48, v180, v48
	ds_bpermute_b32 v49, v180, v49
	ds_bpermute_b32 v38, v180, v38
	ds_bpermute_b32 v39, v180, v39
	ds_bpermute_b32 v40, v180, v40
	ds_bpermute_b32 v41, v180, v41
	v_fmamk_f32 v34, v161, 0x3a800000, v236
	v_rsq_f32_e32 v34, v34
	v_add_u32_e32 v36, 0xa0, v156
	v_ashrrev_i32_e32 v37, 31, v36
	v_lshlrev_b64 v[36:37], 13, v[36:37]
	v_pk_fma_f32 v[32:33], v[32:33], v[34:35], v[144:145] op_sel_hi:[1,0,1]
	v_pk_fma_f32 v[30:31], v[30:31], v[34:35], v[142:143] op_sel_hi:[1,0,1]
	v_pk_fma_f32 v[26:27], v[26:27], v[34:35], v[138:139] op_sel_hi:[1,0,1]
	v_max_f32_e32 v30, 0, v30
	v_max_f32_e32 v31, 0, v31
	v_max_f32_e32 v32, 0, v32
	v_max_f32_e32 v33, 0, v33
	v_pk_fma_f32 v[28:29], v[28:29], v[34:35], v[140:141] op_sel_hi:[1,0,1]
	v_max_f32_e32 v26, 0, v26
	v_max_f32_e32 v27, 0, v27
	v_pk_fma_f32 v[24:25], v[24:25], v[34:35], v[136:137] op_sel_hi:[1,0,1]
	v_pk_fma_f32 v[22:23], v[22:23], v[34:35], v[134:135] op_sel_hi:[1,0,1]
	v_pk_fma_f32 v[20:21], v[20:21], v[34:35], v[132:133] op_sel_hi:[1,0,1]
	v_pk_fma_f32 v[18:19], v[18:19], v[34:35], v[130:131] op_sel_hi:[1,0,1]
	v_pk_mul_f32 v[30:31], v[30:31], v[30:31]
	v_pk_mul_f32 v[32:33], v[32:33], v[32:33]
	v_pk_mul_f32 v[26:27], v[26:27], v[26:27]
	v_max_f32_e32 v28, 0, v28
	v_max_f32_e32 v29, 0, v29
	v_max_f32_e32 v22, 0, v22
	v_max_f32_e32 v23, 0, v23
	v_max_f32_e32 v24, 0, v24
	v_max_f32_e32 v25, 0, v25
	v_max_f32_e32 v18, 0, v18
	v_max_f32_e32 v19, 0, v19
	v_max_f32_e32 v20, 0, v20
	v_max_f32_e32 v21, 0, v21
	v_cvt_pk_bf16_f32 v30, v30, v31
	v_cvt_pk_bf16_f32 v31, v32, v33
	v_pk_mul_f32 v[28:29], v[28:29], v[28:29]
	v_cvt_pk_bf16_f32 v32, v26, v27
	v_lshl_add_u64 v[26:27], s[84:85], 0, v[36:37]
	v_pk_mul_f32 v[22:23], v[22:23], v[22:23]
	v_pk_mul_f32 v[24:25], v[24:25], v[24:25]
	v_pk_mul_f32 v[18:19], v[18:19], v[18:19]
	v_pk_mul_f32 v[20:21], v[20:21], v[20:21]
	v_cvt_pk_bf16_f32 v33, v28, v29
	v_lshl_add_u64 v[26:27], v[26:27], 0, v[122:123]
	v_cvt_pk_bf16_f32 v22, v22, v23
	v_cvt_pk_bf16_f32 v23, v24, v25
	v_cvt_pk_bf16_f32 v24, v18, v19
	v_cvt_pk_bf16_f32 v25, v20, v21
	s_waitcnt lgkmcnt(0)
; #define BAR __builtin_amdgcn_s_barrier()
; template <int EPI>
; DI void gemm_epilogue(const Params& p, int layer, f32x4 (&acc)[2][2][4][2], int brow, int bcol, int pn, int wr, int wc,
;                       int fr, int fq, char* smem, int ksplit = -1) {
;     ...
; #pragma unroll
;     for (int ai = 0; ai < 2; ++ai)
; #pragma unroll
;       for (int m = 0; m < 4; ++m) {
;         __builtin_amdgcn_sched_barrier(0);
;         const int row = brow + ai * 128 + wr * 64 + m * 16 + fr;
;         const float rs = __builtin_amdgcn_rsqf(rsv[ai][m] * (1.f / DM) + EPSN);
; #pragma unroll
;         for (int bj = 0; bj < 2; ++bj) {
;           u32x4 o;
; #pragma unroll
;           for (int n = 0; n < 2; ++n) {
;             f32x4 v = acc[ai][bj][m][n] * rs + bv[bj][n];
; #pragma unroll
;             for (int j = 0; j < 4; ++j) {
;               float r = fmaxf(v[j], 0.f);
;               v[j] = r * r;
;             }
;             o[2 * n] = pk_bf16(v[0], v[1]);
;             o[2 * n + 1] = pk_bf16(v[2], v[3]);
;           }
;           *(u32x4*)(p.hid + (size_t)row * HID + colb + bj * 128) = o;
;         }
;     ...
;     if (!has_next) break;
; #pragma unroll
;     for (int a = 0; a < 2; ++a)
; #pragma unroll
;       for (int b = 0; b < 2; ++b)
; #pragma unroll
;         for (int m = 0; m < 4; ++m)
; #pragma unroll
;           for (int n = 0; n < 2; ++n) acc[a][b][m][n] = (f32x4){0.f, 0.f, 0.f, 0.f};
;     pm = npm; pn = npn; kq = nkq; cA = nA; cB = nB; ++ui;
;     if (wr == 1) BAR;
	global_store_dwordx4 v[42:43], v[46:49], off
	global_store_dwordx4 v[42:43], v[38:41], off offset:256
	ds_bpermute_b32 v30, v180, v30
	ds_bpermute_b32 v31, v180, v31
	ds_bpermute_b32 v32, v180, v32
	ds_bpermute_b32 v33, v180, v33
	ds_bpermute_b32 v22, v180, v22
	ds_bpermute_b32 v23, v180, v23
	ds_bpermute_b32 v24, v180, v24
	ds_bpermute_b32 v25, v180, v25
	v_fmamk_f32 v18, v160, 0x3a800000, v236
	v_rsq_f32_e32 v18, v18
	v_add_u32_e32 v20, 0xb0, v156
	v_ashrrev_i32_e32 v21, 31, v20
	v_lshlrev_b64 v[20:21], 13, v[20:21]
	v_pk_fma_f32 v[16:17], v[16:17], v[18:19], v[144:145] op_sel_hi:[1,0,1]
	v_pk_fma_f32 v[14:15], v[14:15], v[18:19], v[142:143] op_sel_hi:[1,0,1]
	v_pk_fma_f32 v[10:11], v[10:11], v[18:19], v[138:139] op_sel_hi:[1,0,1]
	v_max_f32_e32 v14, 0, v14
	v_max_f32_e32 v15, 0, v15
	v_max_f32_e32 v16, 0, v16
	v_max_f32_e32 v17, 0, v17
	v_pk_fma_f32 v[12:13], v[12:13], v[18:19], v[140:141] op_sel_hi:[1,0,1]
	v_max_f32_e32 v10, 0, v10
	v_max_f32_e32 v11, 0, v11
	v_pk_fma_f32 v[8:9], v[8:9], v[18:19], v[136:137] op_sel_hi:[1,0,1]
	v_pk_fma_f32 v[6:7], v[6:7], v[18:19], v[134:135] op_sel_hi:[1,0,1]
	v_pk_fma_f32 v[4:5], v[4:5], v[18:19], v[132:133] op_sel_hi:[1,0,1]
	v_pk_fma_f32 v[2:3], v[2:3], v[18:19], v[130:131] op_sel_hi:[1,0,1]
	v_pk_mul_f32 v[14:15], v[14:15], v[14:15]
	v_pk_mul_f32 v[16:17], v[16:17], v[16:17]
	v_pk_mul_f32 v[10:11], v[10:11], v[10:11]
	v_max_f32_e32 v12, 0, v12
	v_max_f32_e32 v13, 0, v13
	v_max_f32_e32 v6, 0, v6
	v_max_f32_e32 v7, 0, v7
	v_max_f32_e32 v8, 0, v8
	v_max_f32_e32 v9, 0, v9
	v_max_f32_e32 v2, 0, v2
	v_max_f32_e32 v3, 0, v3
	v_max_f32_e32 v4, 0, v4
	v_max_f32_e32 v5, 0, v5
	v_cvt_pk_bf16_f32 v14, v14, v15
	v_cvt_pk_bf16_f32 v15, v16, v17
	v_pk_mul_f32 v[12:13], v[12:13], v[12:13]
	v_cvt_pk_bf16_f32 v16, v10, v11
	v_lshl_add_u64 v[10:11], s[84:85], 0, v[20:21]
	v_pk_mul_f32 v[6:7], v[6:7], v[6:7]
	v_pk_mul_f32 v[8:9], v[8:9], v[8:9]
	v_pk_mul_f32 v[2:3], v[2:3], v[2:3]
	v_pk_mul_f32 v[4:5], v[4:5], v[4:5]
	v_cvt_pk_bf16_f32 v17, v12, v13
	v_lshl_add_u64 v[10:11], v[10:11], 0, v[122:123]
	v_cvt_pk_bf16_f32 v6, v6, v7
	v_cvt_pk_bf16_f32 v7, v8, v9
	v_cvt_pk_bf16_f32 v8, v2, v3
	v_cvt_pk_bf16_f32 v9, v4, v5
	s_andn2_b64 vcc, exec, s[0:1]
	s_mov_b64 s[0:1], -1
	s_waitcnt lgkmcnt(0)
	global_store_dwordx4 v[26:27], v[30:33], off
	global_store_dwordx4 v[26:27], v[22:25], off offset:256
	ds_bpermute_b32 v14, v180, v14
	ds_bpermute_b32 v15, v180, v15
	ds_bpermute_b32 v16, v180, v16
	ds_bpermute_b32 v17, v180, v17
	ds_bpermute_b32 v6, v180, v6
	ds_bpermute_b32 v7, v180, v7
	ds_bpermute_b32 v8, v180, v8
	ds_bpermute_b32 v9, v180, v9
	s_waitcnt lgkmcnt(0)
	global_store_dwordx4 v[10:11], v[14:17], off
	global_store_dwordx4 v[10:11], v[6:9], off offset:256
	s_cbranch_vccnz .LBB0_990
	s_andn2_b64 vcc, exec, s[4:5]
	s_cbranch_vccnz .LBB0_989
	s_barrier
	s_branch .LBB0_989
